# post-phase row loops: late modulation/gain vector loads hoisted to the iteration top with counted vmcnt waits (5 loops)
# speedup vs baseline: 1.1207x; 1.0113x over previous
.LBB0_41:
	s_add_u32 s0, s68, 0x14100000
	s_addc_u32 s1, s69, 0
	v_writelane_b32 v241, s0, 34
	s_cmp_gt_i32 s70, 1
	v_mov_b32_e32 v184, 0
	v_writelane_b32 v241, s1, 35
	s_cselect_b64 s[0:1], -1, 0
	s_cmp_lt_i32 s71, 2
	s_cselect_b64 s[2:3], -1, 0
	s_or_b64 s[0:1], s[0:1], s[2:3]
	s_and_b64 vcc, exec, s[0:1]
	v_lshrrev_b32_e32 v183, 6, v178
	v_mov_b32_e32 v185, 0
	s_cbranch_vccnz .LBB0_57
	v_and_b32_e32 v0, 12, v183
	v_readlane_b32 s0, v241, 0
	s_nop 1
	v_lshl_add_u32 v0, s0, 3, v0
	v_and_or_b32 v0, v183, 3, v0
	s_movk_i32 s0, 0x6000
	v_cmp_gt_i32_e32 vcc, s0, v0
	s_and_saveexec_b64 s[0:1], vcc
	s_cbranch_execz .LBB0_45
	v_lshlrev_b32_e32 v1, 2, v178
	v_and_b32_e32 v8, 0xfc, v1
	v_mbcnt_lo_u32_b32 v1, -1, 0
	v_mbcnt_hi_u32_b32 v1, -1, v1
	v_and_b32_e32 v2, 64, v1
	v_add_u32_e32 v2, 64, v2
	v_xor_b32_e32 v4, 32, v1
	v_cmp_lt_i32_e32 vcc, v4, v2
	s_add_u32 s6, s68, 0x14000000
	s_addc_u32 s7, s69, 0
	v_cndmask_b32_e32 v4, v1, v4, vcc
	v_lshlrev_b32_e32 v16, 2, v4
	v_xor_b32_e32 v4, 16, v1
	v_cmp_lt_i32_e32 vcc, v4, v2
	s_add_u32 s10, s68, 0x13000000
	v_readlane_b32 s16, v241, 1
	v_cndmask_b32_e32 v4, v1, v4, vcc
	v_lshlrev_b32_e32 v17, 2, v4
	v_xor_b32_e32 v4, 8, v1
	v_cmp_lt_i32_e32 vcc, v4, v2
	s_addc_u32 s11, s69, 0
	v_mov_b32_e32 v3, 0
	v_cndmask_b32_e32 v4, v1, v4, vcc
	v_lshlrev_b32_e32 v18, 2, v4
	v_xor_b32_e32 v4, 4, v1
	v_cmp_lt_i32_e32 vcc, v4, v2
	v_readlane_b32 s17, v241, 2
	v_readlane_b32 s18, v241, 3
	v_cndmask_b32_e32 v4, v1, v4, vcc
	v_lshlrev_b32_e32 v19, 2, v4
	v_xor_b32_e32 v4, 2, v1
	v_cmp_lt_i32_e32 vcc, v4, v2
	v_readlane_b32 s19, v241, 4
	v_readlane_b32 s20, v241, 5
	v_cndmask_b32_e32 v4, v1, v4, vcc
	v_lshlrev_b32_e32 v20, 2, v4
	v_xor_b32_e32 v4, 1, v1
	v_cmp_lt_i32_e32 vcc, v4, v2
	v_lshlrev_b32_e32 v2, 2, v8
	v_readlane_b32 s21, v241, 6
	v_readlane_b32 s22, v241, 7
	v_readlane_b32 s23, v241, 8
	v_readlane_b32 s24, v241, 9
	v_readlane_b32 s25, v241, 10
	v_readlane_b32 s26, v241, 11
	v_readlane_b32 s27, v241, 12
	v_readlane_b32 s28, v241, 13
	v_readlane_b32 s29, v241, 14
	v_readlane_b32 s30, v241, 15
	v_readlane_b32 s31, v241, 16
	s_add_u32 s12, s94, 0x12000000
	v_cndmask_b32_e32 v1, v1, v4, vcc
	v_lshl_add_u64 v[4:5], s[20:21], 0, v[2:3]
	v_readlane_b32 s16, v241, 18
	s_addc_u32 s13, s95, 0
	s_lshl_b32 s2, s78, 3
	v_or_b32_e32 v10, 0x100, v8
	v_or_b32_e32 v12, 0x200, v8
	v_or_b32_e32 v14, 0x300, v8
	v_readlane_b32 s17, v241, 19
	v_readlane_b32 s18, v241, 20
	v_readlane_b32 s19, v241, 21
	v_lshlrev_b32_e32 v21, 2, v1
	v_ashrrev_i32_e32 v1, 31, v0
	s_ashr_i32 s3, s2, 31
	s_mov_b64 s[4:5], 0
	s_movk_i32 s8, 0x2000
	v_mov_b32_e32 v22, s19
	v_mov_b32_e32 v23, s17
	v_mov_b32_e32 v24, s18
	v_mov_b32_e32 v25, s16
	v_lshlrev_b32_e32 v2, 2, v8
	s_movk_i32 s9, 0x3000
	v_mov_b64_e32 v[6:7], s[6:7]
	s_mov_b64 s[6:7], 0x1000
	v_mov_b32_e32 v26, s13
	v_mov_b32_e32 v27, s11
	v_mov_b32_e32 v28, s12
	v_mov_b32_e32 v29, s10
	v_lshlrev_b32_e32 v8, 1, v8
	v_mov_b32_e32 v9, v3
	v_lshlrev_b32_e32 v10, 2, v10
	v_mov_b32_e32 v11, v3
	v_lshlrev_b32_e32 v12, 2, v12
	v_mov_b32_e32 v13, v3
	v_lshlrev_b32_e32 v14, 2, v14
	v_mov_b32_e32 v15, v3
	v_mov_b32_e32 v30, 0x358637bd
	s_mov_b32 s10, 0x800000
	s_movk_i32 s11, 0x5fff
	v_readlane_b32 s20, v241, 22
	v_readlane_b32 s21, v241, 23
	v_readlane_b32 s22, v241, 24
	v_readlane_b32 s23, v241, 25
	v_readlane_b32 s24, v241, 26
	v_readlane_b32 s25, v241, 27
	v_readlane_b32 s26, v241, 28
	v_readlane_b32 s27, v241, 29
	v_readlane_b32 s28, v241, 30
	v_readlane_b32 s29, v241, 31
	v_readlane_b32 s30, v241, 32
	v_readlane_b32 s31, v241, 33
	s_waitcnt vmcnt(0)
.LBB0_44:
	v_add_u32_e32 v31, 0xffffe000, v0
	v_lshrrev_b32_e32 v36, 11, v31
	v_add_u32_e32 v36, 1, v36
	v_cmp_gt_i32_e32 vcc, s8, v0
	global_load_dwordx4 v[32:35], v[4:5], off
	s_nop 0
	v_cndmask_b32_e64 v44, v36, 0, vcc
	v_cndmask_b32_e32 v37, 0, v1, vcc
	v_cndmask_b32_e32 v36, v31, v0, vcc
	v_cndmask_b32_e32 v39, v22, v23, vcc
	v_cndmask_b32_e32 v38, v24, v25, vcc
	v_lshlrev_b64 v[42:43], 12, v[36:37]
	v_mad_u64_u32 v[44:45], s[12:13], v44, s9, v[6:7]
	v_cndmask_b32_e32 v41, v26, v27, vcc
	v_cndmask_b32_e32 v40, v28, v29, vcc
	v_lshlrev_b64 v[36:37], 11, v[36:37]
	v_lshl_add_u64 v[38:39], v[38:39], 0, v[42:43]
	v_lshl_add_u64 v[60:61], v[44:45], 0, s[6:7]
	v_lshl_add_u64 v[40:41], v[40:41], 0, v[36:37]
	v_lshl_add_u64 v[62:63], v[44:45], 0, v[2:3]
	v_lshl_add_u64 v[52:53], v[38:39], 0, v[2:3]
	v_lshl_add_u64 v[56:57], v[60:61], 0, v[2:3]
	global_load_dwordx4 v[36:39], v[62:63], off
	v_lshl_add_u64 v[64:65], v[40:41], 0, v[8:9]
	global_load_dwordx4 v[40:43], v[52:53], off
	global_load_dwordx4 v[44:47], v[52:53], off offset:1024
	global_load_dwordx4 v[48:51], v[52:53], off offset:2048
	s_nop 0
	global_load_dwordx4 v[52:55], v[52:53], off offset:3072
	s_nop 0
	global_load_dwordx4 v[56:59], v[56:57], off
	v_lshl_add_u64 v[66:67], v[60:61], 0, v[10:11]
	v_lshl_add_u64 v[0:1], v[0:1], 0, s[2:3]
	s_waitcnt vmcnt(4)
	v_mov_b32_e32 v74, v41
	s_waitcnt vmcnt(3)
	v_mov_b32_e32 v75, v45
	v_mov_b32_e32 v72, v40
	v_mov_b32_e32 v73, v44
	s_waitcnt vmcnt(2)
	v_mov_b32_e32 v82, v49
	s_waitcnt vmcnt(1)
	v_mov_b32_e32 v83, v53
	v_pk_mul_f32 v[74:75], v[74:75], v[74:75]
	v_mov_b32_e32 v68, v42
	v_mov_b32_e32 v69, v46
	v_mov_b32_e32 v80, v48
	v_mov_b32_e32 v81, v52
	v_pk_mul_f32 v[82:83], v[82:83], v[82:83]
	v_pk_fma_f32 v[72:73], v[72:73], v[72:73], v[74:75]
	v_mov_b32_e32 v70, v43
	v_mov_b32_e32 v71, v47
	v_mov_b32_e32 v76, v50
	v_mov_b32_e32 v77, v54
	v_pk_fma_f32 v[74:75], v[80:81], v[80:81], v[82:83]
	v_pk_fma_f32 v[68:69], v[68:69], v[68:69], v[72:73]
	v_mov_b32_e32 v78, v51
	v_mov_b32_e32 v79, v55
	v_pk_fma_f32 v[72:73], v[76:77], v[76:77], v[74:75]
	v_pk_fma_f32 v[68:69], v[70:71], v[70:71], v[68:69]
	v_pk_fma_f32 v[70:71], v[78:79], v[78:79], v[72:73]
	v_add_f32_e32 v31, v68, v69
	v_add_f32_e32 v31, v31, v70
	v_add_f32_e32 v31, v31, v71
	ds_bpermute_b32 v68, v16, v31
	global_load_dwordx4 v[144:147], v[4:5], off offset:1024
	global_load_dwordx4 v[148:151], v[66:67], off
	global_load_dwordx4 v[156:159], v[62:63], off offset:1024
	global_load_dwordx4 v[164:167], v[4:5], off offset:2048
	v_lshl_add_u64 v[154:155], v[60:61], 0, v[12:13]
	global_load_dwordx4 v[168:171], v[154:155], off
	global_load_dwordx4 v[188:191], v[62:63], off offset:2048
	global_load_dwordx4 v[192:195], v[4:5], off offset:3072
	v_lshl_add_u64 v[154:155], v[60:61], 0, v[14:15]
	global_load_dwordx4 v[196:199], v[154:155], off
	global_load_dwordx4 v[200:203], v[62:63], off offset:3072
	s_waitcnt vmcnt(9)
	v_pk_add_f32 v[56:57], v[56:57], 1.0 op_sel_hi:[1,0]
	v_pk_add_f32 v[58:59], v[58:59], 1.0 op_sel_hi:[1,0]
	s_waitcnt lgkmcnt(0)
	v_add_f32_e32 v31, v31, v68
	ds_bpermute_b32 v68, v17, v31
	s_waitcnt lgkmcnt(0)
	v_add_f32_e32 v31, v31, v68
	ds_bpermute_b32 v68, v18, v31
	s_waitcnt lgkmcnt(0)
	v_add_f32_e32 v31, v31, v68
	ds_bpermute_b32 v68, v19, v31
	s_waitcnt lgkmcnt(0)
	v_add_f32_e32 v31, v31, v68
	ds_bpermute_b32 v68, v20, v31
	s_waitcnt lgkmcnt(0)
	v_add_f32_e32 v31, v31, v68
	ds_bpermute_b32 v68, v21, v31
	s_waitcnt lgkmcnt(0)
	v_add_f32_e32 v31, v31, v68
	v_fmamk_f32 v31, v31, 0x3a800000, v30
	v_mul_f32_e32 v68, 0x4b800000, v31
	v_cmp_gt_f32_e32 vcc, s10, v31
	s_nop 1
	v_cndmask_b32_e32 v31, v31, v68, vcc
	v_rsq_f32_e32 v31, v31
	s_nop 0
	v_mul_f32_e32 v68, 0x45800000, v31
	v_cndmask_b32_e32 v68, v31, v68, vcc
	v_pk_mul_f32 v[40:41], v[40:41], v[68:69] op_sel_hi:[1,0]
	v_pk_mul_f32 v[42:43], v[42:43], v[68:69] op_sel_hi:[1,0]
	v_pk_mul_f32 v[32:33], v[32:33], v[40:41]
	v_pk_mul_f32 v[34:35], v[42:43], v[34:35]
	v_pk_fma_f32 v[32:33], v[56:57], v[32:33], v[36:37]
	v_pk_fma_f32 v[34:35], v[58:59], v[34:35], v[38:39]
	v_cvt_pk_bf16_f32 v32, v32, v33
	v_cvt_pk_bf16_f32 v33, v34, v35
	global_store_dwordx2 v[64:65], v[32:33], off
	s_nop 0
	v_pk_mul_f32 v[44:45], v[44:45], v[68:69] op_sel_hi:[1,0]
	v_pk_mul_f32 v[46:47], v[46:47], v[68:69] op_sel_hi:[1,0]
	v_lshl_add_u64 v[56:57], v[60:61], 0, v[12:13]
	v_cmp_lt_i32_e32 vcc, s11, v0
	s_or_b64 s[4:5], vcc, s[4:5]
	s_waitcnt vmcnt(9)
	v_pk_mul_f32 v[32:33], v[44:45], v[144:145]
	s_waitcnt vmcnt(8)
	v_pk_add_f32 v[36:37], v[148:149], 1.0 op_sel_hi:[1,0]
	v_pk_mul_f32 v[34:35], v[46:47], v[146:147]
	v_pk_add_f32 v[38:39], v[150:151], 1.0 op_sel_hi:[1,0]
	s_waitcnt vmcnt(7)
	v_pk_fma_f32 v[32:33], v[36:37], v[32:33], v[156:157]
	v_pk_fma_f32 v[34:35], v[38:39], v[34:35], v[158:159]
	v_cvt_pk_bf16_f32 v32, v32, v33
	v_cvt_pk_bf16_f32 v33, v34, v35
	global_store_dwordx2 v[64:65], v[32:33], off offset:512
	s_nop 0
	v_pk_mul_f32 v[46:47], v[48:49], v[68:69] op_sel_hi:[1,0]
	v_pk_mul_f32 v[48:49], v[50:51], v[68:69] op_sel_hi:[1,0]
	v_lshl_add_u64 v[44:45], v[60:61], 0, v[14:15]
	s_waitcnt vmcnt(7)
	v_pk_mul_f32 v[32:33], v[46:47], v[164:165]
	s_waitcnt vmcnt(6)
	v_pk_add_f32 v[36:37], v[168:169], 1.0 op_sel_hi:[1,0]
	v_pk_mul_f32 v[34:35], v[48:49], v[166:167]
	v_pk_add_f32 v[38:39], v[170:171], 1.0 op_sel_hi:[1,0]
	s_waitcnt vmcnt(5)
	v_pk_fma_f32 v[32:33], v[36:37], v[32:33], v[188:189]
	v_pk_fma_f32 v[34:35], v[38:39], v[34:35], v[190:191]
	v_cvt_pk_bf16_f32 v32, v32, v33
	v_cvt_pk_bf16_f32 v33, v34, v35
	global_store_dwordx2 v[64:65], v[32:33], off offset:1024
	s_nop 0
	v_pk_mul_f32 v[44:45], v[52:53], v[68:69] op_sel_hi:[1,0]
	v_pk_mul_f32 v[46:47], v[54:55], v[68:69] op_sel_hi:[1,0]
	s_waitcnt vmcnt(5)
	v_pk_mul_f32 v[32:33], v[44:45], v[192:193]
	s_waitcnt vmcnt(4)
	v_pk_add_f32 v[36:37], v[196:197], 1.0 op_sel_hi:[1,0]
	v_pk_mul_f32 v[34:35], v[46:47], v[194:195]
	v_pk_add_f32 v[38:39], v[198:199], 1.0 op_sel_hi:[1,0]
	s_waitcnt vmcnt(3)
	v_pk_fma_f32 v[32:33], v[36:37], v[32:33], v[200:201]
	v_pk_fma_f32 v[34:35], v[38:39], v[34:35], v[202:203]
	v_cvt_pk_bf16_f32 v32, v32, v33
	v_cvt_pk_bf16_f32 v33, v34, v35
	global_store_dwordx2 v[64:65], v[32:33], off offset:1536
	s_andn2_b64 exec, exec, s[4:5]
	s_cbranch_execnz .LBB0_44

.LBB0_754:
	s_cmp_gt_i32 s70, 5
	s_cselect_b64 s[0:1], -1, 0
	s_cmp_lt_i32 s71, 6
	s_cselect_b64 s[2:3], -1, 0
	s_or_b64 s[0:1], s[0:1], s[2:3]
	s_and_b64 vcc, exec, s[0:1]
	s_cbranch_vccnz .LBB0_777
	v_readlane_b32 s0, v241, 0
	s_lshl_b32 s18, s0, 3
	v_and_b32_e32 v0, 12, v183
	v_add_u32_e32 v0, s18, v0
	v_and_or_b32 v8, v183, 3, v0
	s_movk_i32 s0, 0x6000
	v_cmp_gt_i32_e32 vcc, s0, v8
	s_and_saveexec_b64 s[2:3], vcc
	s_cbranch_execz .LBB0_758
	v_mbcnt_lo_u32_b32 v1, -1, 0
	v_mbcnt_hi_u32_b32 v1, -1, v1
	v_and_b32_e32 v3, 64, v1
	v_add_u32_e32 v3, 64, v3
	v_xor_b32_e32 v5, 32, v1
	v_cmp_lt_i32_e32 vcc, v5, v3
	s_add_u32 s4, s68, 0x14000000
	s_addc_u32 s5, s69, 0
	v_cndmask_b32_e32 v5, v1, v5, vcc
	v_lshlrev_b32_e32 v11, 2, v5
	v_xor_b32_e32 v5, 16, v1
	v_cmp_lt_i32_e32 vcc, v5, v3
	s_add_u32 s19, s68, 0x13000000
	s_addc_u32 s20, s69, 0
	v_cndmask_b32_e32 v5, v1, v5, vcc
	v_lshlrev_b32_e32 v40, 2, v5
	v_xor_b32_e32 v5, 8, v1
	v_cmp_lt_i32_e32 vcc, v5, v3
	s_add_u32 s21, s94, 0x12000000
	v_readlane_b32 s36, v241, 1
	v_cndmask_b32_e32 v5, v1, v5, vcc
	v_lshlrev_b32_e32 v41, 2, v5
	v_xor_b32_e32 v5, 4, v1
	v_cmp_lt_i32_e32 vcc, v5, v3
	s_addc_u32 s22, s95, 0
	v_lshlrev_b32_e32 v0, 2, v178
	v_cndmask_b32_e32 v5, v1, v5, vcc
	v_lshlrev_b32_e32 v42, 2, v5
	v_xor_b32_e32 v5, 2, v1
	v_cmp_lt_i32_e32 vcc, v5, v3
	s_lshl_b32 s6, s78, 3
	v_readlane_b32 s40, v241, 5
	v_cndmask_b32_e32 v5, v1, v5, vcc
	v_lshlrev_b32_e32 v43, 2, v5
	v_xor_b32_e32 v5, 1, v1
	v_cmp_lt_i32_e32 vcc, v5, v3
	v_and_b32_e32 v10, 0xfc, v0
	v_readlane_b32 s41, v241, 6
	v_cndmask_b32_e32 v1, v1, v5, vcc
	s_add_u32 s0, s40, 0x1000
	v_ashrrev_i32_e32 v9, 31, v8
	v_mov_b32_e32 v13, 0
	v_or_b32_e32 v0, 0x100, v10
	v_lshlrev_b32_e32 v44, 2, v1
	v_lshlrev_b32_e32 v12, 2, v10
	v_readlane_b32 s42, v241, 7
	v_readlane_b32 s43, v241, 8
	s_addc_u32 s1, s41, 0
	v_lshlrev_b64 v[6:7], 12, v[8:9]
	v_and_b32_e32 v1, 63, v178
	s_waitcnt lgkmcnt(0)
	v_or_b32_e32 v2, 0x200, v10
	v_readlane_b32 s37, v241, 2
	v_readlane_b32 s38, v241, 3
	v_readlane_b32 s39, v241, 4
	v_readlane_b32 s44, v241, 9
	v_readlane_b32 s45, v241, 10
	v_readlane_b32 s46, v241, 11
	v_readlane_b32 s47, v241, 12
	v_readlane_b32 s48, v241, 13
	v_readlane_b32 s49, v241, 14
	v_readlane_b32 s50, v241, 15
	v_readlane_b32 s51, v241, 16
	v_lshl_add_u64 v[14:15], s[42:43], 0, v[12:13]
	v_lshl_add_u64 v[16:17], s[0:1], 0, v[12:13]
	v_lshlrev_b32_e32 v12, 2, v0
	v_lshl_or_b32 v6, v1, 4, v6
	v_or_b32_e32 v4, 0x300, v10
	v_lshl_add_u64 v[18:19], s[0:1], 0, v[12:13]
	v_lshlrev_b32_e32 v12, 2, v2
	v_lshl_add_u64 v[24:25], s[94:95], 0, v[6:7]
	v_lshlrev_b64 v[6:7], 11, v[8:9]
	v_readlane_b32 s36, v241, 18
	v_lshl_add_u64 v[20:21], s[0:1], 0, v[12:13]
	v_lshlrev_b32_e32 v12, 2, v4
	s_ashr_i32 s7, s6, 31
	v_lshl_or_b32 v6, v1, 3, v6
	v_readlane_b32 s37, v241, 19
	v_readlane_b32 s38, v241, 20
	v_readlane_b32 s39, v241, 21
	s_mov_b64 s[8:9], 0x1000
	v_lshl_add_u64 v[22:23], s[0:1], 0, v[12:13]
	s_lshl_b64 s[10:11], s[6:7], 12
	v_lshl_add_u64 v[26:27], s[68:69], 0, v[6:7]
	s_lshl_b64 s[12:13], s[6:7], 11
	s_mov_b64 s[14:15], 0
	s_movk_i32 s23, 0x2000
	s_movk_i32 s24, 0x3000
	s_mov_b64 s[16:17], 0x2000
	v_lshlrev_b32_e32 v28, 2, v0
	v_lshlrev_b32_e32 v30, 2, v2
	v_mov_b32_e32 v31, v13
	v_lshlrev_b32_e32 v32, 2, v4
	v_mov_b32_e32 v33, v13
	v_mov_b32_e32 v45, 0x358637bd
	s_mov_b32 s25, 0x800000
	s_movk_i32 s26, 0x5fff
	v_mov_b32_e32 v46, s39
	v_mov_b32_e32 v47, s37
	v_mov_b32_e32 v48, s38
	v_mov_b32_e32 v49, s36
	v_lshlrev_b32_e32 v34, 2, v10
	v_mov_b32_e32 v35, v13
	v_mov_b32_e32 v29, v13
	v_readlane_b32 s40, v241, 22
	v_readlane_b32 s41, v241, 23
	v_readlane_b32 s42, v241, 24
	v_readlane_b32 s43, v241, 25
	v_readlane_b32 s44, v241, 26
	v_readlane_b32 s45, v241, 27
	v_readlane_b32 s46, v241, 28
	v_readlane_b32 s47, v241, 29
	v_readlane_b32 s48, v241, 30
	v_readlane_b32 s49, v241, 31
	v_readlane_b32 s50, v241, 32
	v_readlane_b32 s51, v241, 33
	s_waitcnt vmcnt(0)
.LBB0_757:
	global_load_dwordx2 v[66:67], v[26:27], off
	global_load_dwordx2 v[68:69], v[26:27], off offset:512
	global_load_dwordx2 v[70:71], v[26:27], off offset:1024
	global_load_dwordx2 v[72:73], v[26:27], off offset:1536
	v_add_u32_e32 v0, 0xffffe000, v8
	v_lshrrev_b32_e32 v1, 11, v0
	v_add_u32_e32 v1, 1, v1
	v_cmp_gt_i32_e32 vcc, s23, v8
	v_mov_b64_e32 v[36:37], s[4:5]
	global_load_dwordx4 v[4:7], v[14:15], off
	v_cndmask_b32_e64 v102, v1, 0, vcc
	v_cndmask_b32_e32 v39, 0, v9, vcc
	v_cndmask_b32_e32 v38, v0, v8, vcc
	v_cndmask_b32_e32 v1, v46, v47, vcc
	v_cndmask_b32_e32 v0, v48, v49, vcc
	v_lshlrev_b64 v[2:3], 12, v[38:39]
	v_mad_u64_u32 v[50:51], s[0:1], v102, s24, v[36:37]
	v_lshl_add_u64 v[0:1], v[0:1], 0, v[2:3]
	v_lshl_add_u64 v[74:75], v[50:51], 0, s[16:17]
	v_lshl_add_u64 v[0:1], v[0:1], 0, v[34:35]
	v_lshl_add_u64 v[2:3], v[74:75], 0, v[34:35]
	global_load_dwordx4 v[50:53], v[2:3], off
	global_load_dwordx4 v[54:57], v[0:1], off
	global_load_dwordx4 v[58:61], v[0:1], off offset:1024
	global_load_dwordx4 v[62:65], v[0:1], off offset:2048
	s_nop 0
	global_load_dwordx4 v[0:3], v[0:1], off offset:3072
	v_lshl_add_u64 v[76:77], v[74:75], 0, v[28:29]
	v_lshlrev_b64 v[38:39], 11, v[38:39]
	v_lshl_add_u64 v[8:9], v[8:9], 0, s[6:7]
	v_lshl_add_u64 v[26:27], v[26:27], 0, s[12:13]
	global_load_dwordx4 v[144:147], v[14:15], off offset:1024
	global_load_dwordx4 v[148:151], v[76:77], off
	global_load_dwordx4 v[156:159], v[14:15], off offset:2048
	v_lshl_add_u64 v[154:155], v[74:75], 0, v[30:31]
	global_load_dwordx4 v[164:167], v[154:155], off
	global_load_dwordx4 v[168:171], v[14:15], off offset:3072
	v_lshl_add_u64 v[154:155], v[74:75], 0, v[32:33]
	global_load_dwordx4 v[188:191], v[154:155], off
	global_load_dwordx4 v[192:195], v[16:17], off
	v_mov_b32_e32 v162, v36
	v_mov_b32_e32 v163, v37
	v_add_u32_e32 v160, 9, v102
	v_mad_u64_u32 v[162:163], s[98:99], v160, s24, v[162:163]
	v_lshl_add_u64 v[196:197], v[162:163], 0, s[8:9]
	v_lshl_add_u64 v[154:155], v[196:197], 0, v[34:35]
	global_load_dwordx4 v[200:203], v[154:155], off
	v_mov_b32_e32 v162, v36
	v_mov_b32_e32 v163, v37
	v_add_u32_e32 v154, 9, v102
	v_mad_u64_u32 v[162:163], s[98:99], v154, s24, v[162:163]
	v_lshl_add_u64 v[154:155], v[162:163], 0, v[34:35]
	global_load_dwordx4 v[196:199], v[154:155], off
	global_load_dwordx4 v[204:207], v[18:19], off
	v_mov_b32_e32 v162, v36
	v_mov_b32_e32 v163, v37
	v_add_u32_e32 v160, 9, v102
	v_mad_u64_u32 v[162:163], s[98:99], v160, s24, v[162:163]
	v_lshl_add_u64 v[208:209], v[162:163], 0, s[8:9]
	v_lshl_add_u64 v[154:155], v[208:209], 0, v[28:29]
	global_load_dwordx4 v[212:215], v[154:155], off
	v_mov_b32_e32 v162, v36
	v_mov_b32_e32 v163, v37
	v_add_u32_e32 v154, 9, v102
	v_mad_u64_u32 v[162:163], s[98:99], v154, s24, v[162:163]
	v_lshl_add_u64 v[154:155], v[162:163], 0, v[34:35]
	global_load_dwordx4 v[208:211], v[154:155], off offset:1024
	global_load_dwordx4 v[216:219], v[20:21], off
	v_mov_b32_e32 v162, v36
	v_mov_b32_e32 v163, v37
	v_add_u32_e32 v160, 9, v102
	v_mad_u64_u32 v[162:163], s[98:99], v160, s24, v[162:163]
	v_lshl_add_u64 v[220:221], v[162:163], 0, s[8:9]
	v_lshl_add_u64 v[154:155], v[220:221], 0, v[30:31]
	global_load_dwordx4 v[224:227], v[154:155], off
	v_mov_b32_e32 v162, v36
	v_mov_b32_e32 v163, v37
	v_add_u32_e32 v154, 9, v102
	v_mad_u64_u32 v[162:163], s[98:99], v154, s24, v[162:163]
	v_lshl_add_u64 v[154:155], v[162:163], 0, v[34:35]
	global_load_dwordx4 v[220:223], v[154:155], off offset:2048
	global_load_dwordx4 v[228:231], v[22:23], off
	v_mov_b32_e32 v162, v36
	v_mov_b32_e32 v163, v37
	v_add_u32_e32 v160, 9, v102
	v_mad_u64_u32 v[162:163], s[98:99], v160, s24, v[162:163]
	v_lshl_add_u64 v[232:233], v[162:163], 0, s[8:9]
	v_lshl_add_u64 v[154:155], v[232:233], 0, v[32:33]
	global_load_dwordx4 v[236:239], v[154:155], off
	v_mov_b32_e32 v162, v36
	v_mov_b32_e32 v163, v37
	v_add_u32_e32 v154, 9, v102
	v_mad_u64_u32 v[162:163], s[98:99], v154, s24, v[162:163]
	v_lshl_add_u64 v[154:155], v[162:163], 0, v[34:35]
	global_load_dwordx4 v[232:235], v[154:155], off offset:3072
	s_waitcnt vmcnt(27)
	v_and_b32_e32 v79, 0xffff0000, v66
	s_waitcnt vmcnt(26)
	v_and_b32_e32 v81, 0xffff0000, v68
	v_lshlrev_b32_e32 v78, 16, v66
	v_lshlrev_b32_e32 v80, 16, v68
	s_waitcnt vmcnt(25)
	v_and_b32_e32 v83, 0xffff0000, v70
	s_waitcnt vmcnt(24)
	v_and_b32_e32 v85, 0xffff0000, v72
	v_mov_b32_e32 v88, v79
	v_mov_b32_e32 v89, v81
	v_lshlrev_b32_e32 v66, 16, v67
	v_lshlrev_b32_e32 v68, 16, v69
	v_lshlrev_b32_e32 v82, 16, v70
	v_lshlrev_b32_e32 v84, 16, v72
	v_mov_b32_e32 v86, v78
	v_mov_b32_e32 v87, v80
	v_mov_b32_e32 v96, v83
	v_mov_b32_e32 v97, v85
	v_pk_mul_f32 v[88:89], v[88:89], v[88:89]
	v_and_b32_e32 v67, 0xffff0000, v67
	v_and_b32_e32 v69, 0xffff0000, v69
	v_lshlrev_b32_e32 v70, 16, v71
	v_lshlrev_b32_e32 v72, 16, v73
	v_mov_b32_e32 v90, v66
	v_mov_b32_e32 v91, v68
	v_mov_b32_e32 v94, v82
	v_mov_b32_e32 v95, v84
	v_pk_mul_f32 v[96:97], v[96:97], v[96:97]
	v_pk_fma_f32 v[86:87], v[86:87], v[86:87], v[88:89]
	v_and_b32_e32 v71, 0xffff0000, v71
	v_and_b32_e32 v73, 0xffff0000, v73
	v_mov_b32_e32 v92, v67
	v_mov_b32_e32 v93, v69
	v_mov_b32_e32 v98, v70
	v_mov_b32_e32 v99, v72
	v_pk_fma_f32 v[88:89], v[94:95], v[94:95], v[96:97]
	v_pk_fma_f32 v[86:87], v[90:91], v[90:91], v[86:87]
	v_mov_b32_e32 v100, v71
	v_mov_b32_e32 v101, v73
	v_pk_fma_f32 v[88:89], v[98:99], v[98:99], v[88:89]
	v_pk_fma_f32 v[86:87], v[92:93], v[92:93], v[86:87]
	v_pk_fma_f32 v[88:89], v[100:101], v[100:101], v[88:89]
	v_add_f32_e32 v12, v86, v87
	v_add_f32_e32 v12, v12, v88
	v_add_f32_e32 v12, v12, v89
	ds_bpermute_b32 v86, v11, v12
	s_waitcnt lgkmcnt(0)
	v_add_f32_e32 v12, v12, v86
	ds_bpermute_b32 v86, v40, v12
	s_waitcnt lgkmcnt(0)
	v_add_f32_e32 v12, v12, v86
	ds_bpermute_b32 v86, v41, v12
	s_waitcnt lgkmcnt(0)
	v_add_f32_e32 v12, v12, v86
	ds_bpermute_b32 v86, v42, v12
	s_waitcnt lgkmcnt(0)
	v_add_f32_e32 v12, v12, v86
	ds_bpermute_b32 v86, v43, v12
	s_waitcnt lgkmcnt(0)
	v_add_f32_e32 v12, v12, v86
	ds_bpermute_b32 v86, v44, v12
	s_waitcnt lgkmcnt(0)
	v_add_f32_e32 v12, v12, v86
	v_fmamk_f32 v12, v12, 0x3a800000, v45
	v_mul_f32_e32 v86, 0x4b800000, v12
	v_cmp_gt_f32_e64 s[0:1], s25, v12
	s_nop 1
	v_cndmask_b32_e64 v12, v12, v86, s[0:1]
	v_rsq_f32_e32 v12, v12
	s_nop 0
	v_mul_f32_e32 v86, 0x45800000, v12
	v_cndmask_b32_e64 v86, v12, v86, s[0:1]
	v_pk_mul_f32 v[78:79], v[86:87], v[78:79] op_sel_hi:[0,1]
	v_pk_mul_f32 v[66:67], v[86:87], v[66:67] op_sel_hi:[0,1]
	s_waitcnt vmcnt(23)
	v_pk_mul_f32 v[4:5], v[4:5], v[78:79]
	v_pk_mul_f32 v[6:7], v[6:7], v[66:67]
	s_waitcnt vmcnt(21)
	v_pk_fma_f32 v[50:51], v[50:51], v[4:5], v[54:55]
	v_pk_fma_f32 v[52:53], v[52:53], v[6:7], v[56:57]
	global_store_dwordx4 v[24:25], v[50:53], off
	v_pk_mul_f32 v[76:77], v[86:87], v[80:81] op_sel_hi:[0,1]
	v_pk_mul_f32 v[68:69], v[86:87], v[68:69] op_sel_hi:[0,1]
	v_lshl_add_u64 v[66:67], v[74:75], 0, v[30:31]
	v_pk_mul_f32 v[70:71], v[86:87], v[70:71] op_sel_hi:[0,1]
	v_lshlrev_b32_e32 v12, 1, v10
	v_mov_b32_e32 v78, v51
	v_mov_b32_e32 v80, v52
	s_waitcnt vmcnt(18)
	v_pk_mul_f32 v[4:5], v[76:77], v[144:145]
	v_pk_mul_f32 v[6:7], v[68:69], v[146:147]
	s_waitcnt vmcnt(17)
	v_pk_fma_f32 v[54:55], v[148:149], v[4:5], v[58:59]
	v_pk_fma_f32 v[56:57], v[150:151], v[6:7], v[60:61]
	global_store_dwordx4 v[24:25], v[54:57], off offset:1024
	v_pk_mul_f32 v[68:69], v[86:87], v[82:83] op_sel_hi:[0,1]
	v_lshl_add_u64 v[66:67], v[74:75], 0, v[32:33]
	v_mov_b32_e32 v79, v55
	v_pk_mul_f32 v[78:79], v[78:79], v[78:79]
	v_mov_b32_e32 v81, v56
	v_mov_b32_e32 v82, v53
	v_mov_b32_e32 v83, v57
	s_waitcnt vmcnt(17)
	v_pk_mul_f32 v[4:5], v[68:69], v[156:157]
	v_pk_mul_f32 v[6:7], v[70:71], v[158:159]
	s_waitcnt vmcnt(16)
	v_pk_fma_f32 v[4:5], v[164:165], v[4:5], v[62:63]
	v_pk_fma_f32 v[6:7], v[166:167], v[6:7], v[64:65]
	global_store_dwordx4 v[24:25], v[4:7], off offset:2048
	v_mov_b32_e32 v66, s22
	v_mov_b32_e32 v67, s20
	v_mov_b32_e32 v68, s21
	v_mov_b32_e32 v69, s19
	v_cndmask_b32_e32 v67, v66, v67, vcc
	v_cndmask_b32_e32 v66, v68, v69, vcc
	v_add_u32_e32 v68, 9, v102
	v_mad_u64_u32 v[36:37], s[0:1], v68, s24, v[36:37]
	v_lshl_add_u64 v[38:39], v[66:67], 0, v[38:39]
	v_lshl_add_u64 v[66:67], v[36:37], 0, s[8:9]
	v_lshl_add_u64 v[68:69], v[36:37], 0, v[34:35]
	v_lshl_add_u64 v[70:71], v[38:39], 0, v[12:13]
	v_pk_mul_f32 v[36:37], v[86:87], v[84:85] op_sel_hi:[0,1]
	v_pk_mul_f32 v[38:39], v[86:87], v[72:73] op_sel_hi:[0,1]
	v_lshl_add_u64 v[74:75], v[66:67], 0, v[34:35]
	v_mov_b32_e32 v72, v50
	v_mov_b32_e32 v73, v54
	v_pk_fma_f32 v[72:73], v[72:73], v[72:73], v[78:79]
	v_mov_b32_e32 v78, v5
	v_pk_fma_f32 v[72:73], v[80:81], v[80:81], v[72:73]
	v_mov_b32_e32 v80, v6
	v_pk_fma_f32 v[72:73], v[82:83], v[82:83], v[72:73]
	v_lshl_add_u64 v[76:77], v[66:67], 0, v[28:29]
	v_add_f32_e32 v12, v72, v73
	v_mov_b32_e32 v72, v4
	s_waitcnt vmcnt(16)
	v_pk_mul_f32 v[36:37], v[36:37], v[168:169]
	v_pk_mul_f32 v[38:39], v[38:39], v[170:171]
	s_waitcnt vmcnt(15)
	v_pk_fma_f32 v[0:1], v[188:189], v[36:37], v[0:1]
	v_pk_fma_f32 v[2:3], v[190:191], v[38:39], v[2:3]
	global_store_dwordx4 v[24:25], v[0:3], off offset:3072
	v_mov_b32_e32 v79, v1
	v_mov_b32_e32 v73, v0
	v_pk_mul_f32 v[78:79], v[78:79], v[78:79]
	v_mov_b32_e32 v81, v2
	v_pk_fma_f32 v[72:73], v[72:73], v[72:73], v[78:79]
	v_mov_b32_e32 v74, v7
	v_mov_b32_e32 v75, v3
	v_pk_fma_f32 v[72:73], v[80:81], v[80:81], v[72:73]
	v_lshl_add_u64 v[24:25], v[24:25], 0, s[10:11]
	v_pk_fma_f32 v[72:73], v[74:75], v[74:75], v[72:73]
	s_nop 0
	v_add_f32_e32 v12, v12, v72
	v_add_f32_e32 v12, v12, v73
	ds_bpermute_b32 v72, v11, v12
	s_waitcnt lgkmcnt(0)
	v_add_f32_e32 v12, v12, v72
	ds_bpermute_b32 v72, v40, v12
	s_waitcnt lgkmcnt(0)
	v_add_f32_e32 v12, v12, v72
	ds_bpermute_b32 v72, v41, v12
	s_waitcnt lgkmcnt(0)
	v_add_f32_e32 v12, v12, v72
	ds_bpermute_b32 v72, v42, v12
	s_waitcnt lgkmcnt(0)
	v_add_f32_e32 v12, v12, v72
	ds_bpermute_b32 v72, v43, v12
	s_waitcnt lgkmcnt(0)
	v_add_f32_e32 v12, v12, v72
	ds_bpermute_b32 v72, v44, v12
	s_waitcnt lgkmcnt(0)
	v_add_f32_e32 v12, v12, v72
	v_fmamk_f32 v12, v12, 0x3a800000, v45
	v_mul_f32_e32 v72, 0x4b800000, v12
	v_cmp_gt_f32_e32 vcc, s25, v12
	s_nop 1
	v_cndmask_b32_e32 v12, v12, v72, vcc
	v_rsq_f32_e32 v12, v12
	s_nop 0
	v_mul_f32_e32 v72, 0x45800000, v12
	v_cndmask_b32_e32 v12, v12, v72, vcc
	v_pk_mul_f32 v[50:51], v[50:51], v[12:13] op_sel_hi:[1,0]
	v_pk_mul_f32 v[52:53], v[52:53], v[12:13] op_sel_hi:[1,0]
	v_pk_mul_f32 v[54:55], v[54:55], v[12:13] op_sel_hi:[1,0]
	v_pk_mul_f32 v[56:57], v[56:57], v[12:13] op_sel_hi:[1,0]
	v_pk_mul_f32 v[4:5], v[4:5], v[12:13] op_sel_hi:[1,0]
	v_pk_mul_f32 v[6:7], v[6:7], v[12:13] op_sel_hi:[1,0]
	v_pk_mul_f32 v[0:1], v[0:1], v[12:13] op_sel_hi:[1,0]
	v_pk_mul_f32 v[2:3], v[2:3], v[12:13] op_sel_hi:[1,0]
	v_cmp_lt_i32_e32 vcc, s26, v8
	s_or_b64 s[14:15], vcc, s[14:15]
	s_waitcnt vmcnt(15)
	v_pk_mul_f32 v[36:37], v[192:193], v[50:51]
	s_waitcnt vmcnt(14)
	v_pk_add_f32 v[50:51], v[200:201], 1.0 op_sel_hi:[1,0]
	v_pk_mul_f32 v[38:39], v[52:53], v[194:195]
	v_pk_add_f32 v[52:53], v[202:203], 1.0 op_sel_hi:[1,0]
	s_waitcnt vmcnt(13)
	v_pk_fma_f32 v[36:37], v[50:51], v[36:37], v[196:197]
	v_pk_fma_f32 v[38:39], v[52:53], v[38:39], v[198:199]
	v_cvt_pk_bf16_f32 v36, v36, v37
	v_cvt_pk_bf16_f32 v37, v38, v39
	global_store_dwordx2 v[70:71], v[36:37], off
	s_nop 0
	v_lshl_add_u64 v[62:63], v[66:67], 0, v[30:31]
	s_waitcnt vmcnt(13)
	v_pk_mul_f32 v[36:37], v[54:55], v[204:205]
	s_waitcnt vmcnt(12)
	v_pk_add_f32 v[50:51], v[212:213], 1.0 op_sel_hi:[1,0]
	v_pk_mul_f32 v[38:39], v[56:57], v[206:207]
	v_pk_add_f32 v[52:53], v[214:215], 1.0 op_sel_hi:[1,0]
	s_waitcnt vmcnt(11)
	v_pk_fma_f32 v[36:37], v[50:51], v[36:37], v[208:209]
	v_pk_fma_f32 v[38:39], v[52:53], v[38:39], v[210:211]
	v_cvt_pk_bf16_f32 v36, v36, v37
	v_cvt_pk_bf16_f32 v37, v38, v39
	global_store_dwordx2 v[70:71], v[36:37], off offset:512
	s_nop 0
	v_lshl_add_u64 v[58:59], v[66:67], 0, v[32:33]
	s_waitcnt vmcnt(11)
	v_pk_mul_f32 v[4:5], v[4:5], v[216:217]
	s_waitcnt vmcnt(10)
	v_pk_add_f32 v[36:37], v[224:225], 1.0 op_sel_hi:[1,0]
	v_pk_mul_f32 v[6:7], v[6:7], v[218:219]
	v_pk_add_f32 v[38:39], v[226:227], 1.0 op_sel_hi:[1,0]
	s_waitcnt vmcnt(9)
	v_pk_fma_f32 v[4:5], v[36:37], v[4:5], v[220:221]
	v_pk_fma_f32 v[6:7], v[38:39], v[6:7], v[222:223]
	v_cvt_pk_bf16_f32 v4, v4, v5
	v_cvt_pk_bf16_f32 v5, v6, v7
	global_store_dwordx2 v[70:71], v[4:5], off offset:1024
	s_nop 0
	s_waitcnt vmcnt(9)
	v_pk_mul_f32 v[0:1], v[0:1], v[228:229]
	s_waitcnt vmcnt(8)
	v_pk_add_f32 v[4:5], v[236:237], 1.0 op_sel_hi:[1,0]
	v_pk_mul_f32 v[2:3], v[2:3], v[230:231]
	v_pk_add_f32 v[6:7], v[238:239], 1.0 op_sel_hi:[1,0]
	s_waitcnt vmcnt(7)
	v_pk_fma_f32 v[0:1], v[4:5], v[0:1], v[232:233]
	v_pk_fma_f32 v[2:3], v[6:7], v[2:3], v[234:235]
	v_cvt_pk_bf16_f32 v0, v0, v1
	v_cvt_pk_bf16_f32 v1, v2, v3
	global_store_dwordx2 v[70:71], v[0:1], off offset:1536
	s_andn2_b64 exec, exec, s[14:15]
	s_cbranch_execnz .LBB0_757

.LBB0_1205:
	s_cmp_gt_i32 s70, 12
	s_cselect_b64 s[0:1], -1, 0
	s_cmp_lt_i32 s71, 13
	s_cselect_b64 s[2:3], -1, 0
	s_or_b64 s[0:1], s[0:1], s[2:3]
	s_and_b64 vcc, exec, s[0:1]
	s_cbranch_vccnz .LBB0_1228
	v_readlane_b32 s0, v241, 0
	s_lshl_b32 s18, s0, 3
	v_and_b32_e32 v0, 12, v183
	v_add_u32_e32 v0, s18, v0
	s_waitcnt lgkmcnt(0)
	v_and_or_b32 v4, v183, 3, v0
	s_movk_i32 s0, 0x6000
	v_cmp_gt_i32_e32 vcc, s0, v4
	s_and_saveexec_b64 s[2:3], vcc
	s_cbranch_execz .LBB0_1209
	v_mbcnt_lo_u32_b32 v1, -1, 0
	v_mbcnt_hi_u32_b32 v1, -1, v1
	v_and_b32_e32 v3, 64, v1
	v_add_u32_e32 v3, 64, v3
	v_xor_b32_e32 v5, 32, v1
	v_cmp_lt_i32_e32 vcc, v5, v3
	s_add_u32 s4, s68, 0x14000000
	s_addc_u32 s5, s69, 0
	v_cndmask_b32_e32 v5, v1, v5, vcc
	v_lshlrev_b32_e32 v7, 2, v5
	v_xor_b32_e32 v5, 16, v1
	v_cmp_lt_i32_e32 vcc, v5, v3
	s_add_u32 s19, s68, 0x13000000
	s_addc_u32 s20, s69, 0
	v_cndmask_b32_e32 v5, v1, v5, vcc
	v_lshlrev_b32_e32 v40, 2, v5
	v_xor_b32_e32 v5, 8, v1
	v_cmp_lt_i32_e32 vcc, v5, v3
	s_add_u32 s21, s94, 0x12000000
	v_lshlrev_b32_e32 v0, 2, v178
	v_cndmask_b32_e32 v5, v1, v5, vcc
	v_lshlrev_b32_e32 v41, 2, v5
	v_xor_b32_e32 v5, 4, v1
	v_cmp_lt_i32_e32 vcc, v5, v3
	v_readlane_b32 s36, v241, 1
	s_addc_u32 s22, s95, 0
	v_cndmask_b32_e32 v5, v1, v5, vcc
	v_lshlrev_b32_e32 v42, 2, v5
	v_xor_b32_e32 v5, 2, v1
	v_cmp_lt_i32_e32 vcc, v5, v3
	v_and_b32_e32 v6, 0xfc, v0
	s_lshl_b32 s6, s78, 3
	v_cndmask_b32_e32 v5, v1, v5, vcc
	v_lshlrev_b32_e32 v43, 2, v5
	v_xor_b32_e32 v5, 1, v1
	v_readlane_b32 s42, v241, 7
	v_mov_b32_e32 v9, 0
	v_or_b32_e32 v0, 0x100, v6
	v_or_b32_e32 v2, 0x200, v6
	v_or_b32_e32 v34, 0x300, v6
	v_cmp_lt_i32_e32 vcc, v5, v3
	v_readlane_b32 s43, v241, 8
	s_add_u32 s0, s42, 0x1000
	v_cndmask_b32_e32 v1, v1, v5, vcc
	v_readlane_b32 s40, v241, 5
	s_addc_u32 s1, s43, 0
	v_lshlrev_b32_e32 v8, 2, v6
	v_lshlrev_b32_e32 v20, 2, v0
	v_mov_b32_e32 v21, v9
	v_lshlrev_b32_e32 v22, 2, v2
	v_mov_b32_e32 v23, v9
	v_lshlrev_b32_e32 v24, 2, v34
	v_mov_b32_e32 v25, v9
	v_ashrrev_i32_e32 v5, 31, v4
	v_lshlrev_b32_e32 v44, 2, v1
	v_readlane_b32 s41, v241, 6
	v_lshl_add_u64 v[10:11], s[0:1], 0, v[8:9]
	v_lshl_add_u64 v[12:13], s[0:1], 0, v[20:21]
	v_lshl_add_u64 v[14:15], s[0:1], 0, v[22:23]
	v_lshl_add_u64 v[16:17], s[0:1], 0, v[24:25]
	s_add_u32 s0, s40, 0x2000
	v_lshlrev_b64 v[26:27], 11, v[4:5]
	v_and_b32_e32 v1, 63, v178
	s_addc_u32 s1, s41, 0
	v_lshl_or_b32 v26, v1, 3, v26
	v_lshlrev_b64 v[28:29], 12, v[4:5]
	v_lshl_add_u64 v[18:19], s[0:1], 0, v[8:9]
	v_lshl_add_u64 v[20:21], s[0:1], 0, v[20:21]
	v_lshl_add_u64 v[22:23], s[0:1], 0, v[22:23]
	v_lshl_add_u64 v[24:25], s[0:1], 0, v[24:25]
	v_lshl_add_u64 v[26:27], s[68:69], 0, v[26:27]
	s_mov_b64 s[0:1], 0x6000000
	v_lshl_or_b32 v28, v1, 4, v28
	s_ashr_i32 s7, s6, 31
	v_lshl_add_u64 v[26:27], v[26:27], 0, s[0:1]
	v_lshl_add_u64 v[28:29], s[94:95], 0, v[28:29]
	s_mov_b64 s[0:1], 0x800
	s_mov_b64 s[8:9], 0x1000
	s_mov_b64 s[10:11], 0x2000
	s_lshl_b64 s[12:13], s[6:7], 11
	v_lshl_add_u64 v[28:29], v[28:29], 0, s[0:1]
	s_lshl_b64 s[14:15], s[6:7], 12
	s_mov_b64 s[16:17], 0
	s_movk_i32 s23, 0x2000
	v_lshlrev_b32_e32 v30, 2, v0
	v_lshlrev_b32_e32 v32, 2, v2
	v_lshlrev_b32_e32 v34, 2, v34
	v_mov_b32_e32 v45, 0x358637bd
	s_mov_b32 s24, 0x800000
	s_movk_i32 s25, 0x5fff
	v_readlane_b32 s37, v241, 2
	v_readlane_b32 s38, v241, 3
	v_readlane_b32 s39, v241, 4
	v_readlane_b32 s44, v241, 9
	v_readlane_b32 s45, v241, 10
	v_readlane_b32 s46, v241, 11
	v_readlane_b32 s47, v241, 12
	v_readlane_b32 s48, v241, 13
	v_readlane_b32 s49, v241, 14
	v_readlane_b32 s50, v241, 15
	v_readlane_b32 s51, v241, 16
	s_waitcnt vmcnt(0)
.LBB0_1208:
	global_load_dwordx2 v[36:37], v[26:27], off
	global_load_dwordx2 v[38:39], v[26:27], off offset:512
	global_load_dwordx2 v[58:59], v[26:27], off offset:1024
	global_load_dwordx2 v[60:61], v[26:27], off offset:1536
	v_add_u32_e32 v90, 0xffffe000, v4
	v_ashrrev_i32_e32 v33, 11, v90
	v_add_u32_e32 v33, 1, v33
	v_cmp_gt_i32_e32 vcc, s23, v4
	v_lshlrev_b32_e32 v8, 2, v6
	global_load_dwordx4 v[0:3], v[10:11], off
	v_cndmask_b32_e64 v91, v33, 0, vcc
	v_add_u32_e32 v33, 9, v91
	v_mul_hi_i32_i24_e32 v55, 0x3000, v33
	v_mul_i32_i24_e32 v54, 0x3000, v33
	v_lshl_add_u64 v[54:55], s[4:5], 0, v[54:55]
	v_mov_b32_e32 v144, v54
	v_mov_b32_e32 v145, v55
	v_lshl_add_u64 v[146:147], v[144:145], 0, s[10:11]
	v_lshl_add_u64 v[144:145], v[146:147], 0, v[8:9]
	global_load_dwordx4 v[148:151], v[144:145], off
	global_load_dwordx4 v[144:147], v[12:13], off
	v_mov_b32_e32 v158, v30
	v_lshl_add_u64 v[156:157], v[54:55], 0, s[10:11]
	v_mov_b32_e32 v159, v9
	v_lshl_add_u64 v[154:155], v[156:157], 0, v[158:159]
	global_load_dwordx4 v[164:167], v[154:155], off
	global_load_dwordx4 v[156:159], v[28:29], off
	global_load_dwordx4 v[168:171], v[14:15], off
	v_mov_b32_e32 v188, v32
	v_lshl_add_u64 v[162:163], v[54:55], 0, s[10:11]
	v_mov_b32_e32 v189, v9
	v_lshl_add_u64 v[154:155], v[162:163], 0, v[188:189]
	global_load_dwordx4 v[192:195], v[154:155], off
	global_load_dwordx4 v[188:191], v[28:29], off offset:1024
	global_load_dwordx4 v[196:199], v[16:17], off
	v_mov_b32_e32 v162, v34
	v_lshl_add_u64 v[154:155], v[54:55], 0, s[10:11]
	v_mov_b32_e32 v163, v9
	v_lshl_add_u64 v[154:155], v[154:155], 0, v[162:163]
	global_load_dwordx4 v[200:203], v[154:155], off
	global_load_dwordx4 v[204:207], v[18:19], off
	v_add_u32_e32 v208, 18, v91
	v_mul_hi_i32_i24_e32 v209, 0x3000, v208
	v_mul_i32_i24_e32 v208, 0x3000, v208
	v_lshl_add_u64 v[162:163], s[4:5], 0, v[208:209]
	v_lshl_add_u64 v[208:209], v[162:163], 0, s[8:9]
	v_lshl_add_u64 v[154:155], v[208:209], 0, v[8:9]
	global_load_dwordx4 v[212:215], v[154:155], off
	v_add_u32_e32 v162, 18, v91
	v_mul_hi_i32_i24_e32 v163, 0x3000, v162
	v_mul_i32_i24_e32 v162, 0x3000, v162
	v_lshl_add_u64 v[154:155], s[4:5], 0, v[162:163]
	v_lshl_add_u64 v[154:155], v[154:155], 0, v[8:9]
	global_load_dwordx4 v[208:211], v[154:155], off
	global_load_dwordx4 v[216:219], v[20:21], off
	v_mov_b32_e32 v222, v30
	v_mov_b32_e32 v223, v9
	v_add_u32_e32 v220, 18, v91
	v_mul_hi_i32_i24_e32 v221, 0x3000, v220
	v_mul_i32_i24_e32 v220, 0x3000, v220
	v_lshl_add_u64 v[162:163], s[4:5], 0, v[220:221]
	v_lshl_add_u64 v[220:221], v[162:163], 0, s[8:9]
	v_lshl_add_u64 v[154:155], v[220:221], 0, v[222:223]
	global_load_dwordx4 v[224:227], v[154:155], off
	v_add_u32_e32 v162, 18, v91
	v_mul_hi_i32_i24_e32 v163, 0x3000, v162
	v_mul_i32_i24_e32 v162, 0x3000, v162
	v_lshl_add_u64 v[154:155], s[4:5], 0, v[162:163]
	v_lshl_add_u64 v[154:155], v[154:155], 0, v[8:9]
	global_load_dwordx4 v[220:223], v[154:155], off offset:1024
	global_load_dwordx4 v[228:231], v[22:23], off
	v_mov_b32_e32 v234, v32
	v_mov_b32_e32 v235, v9
	v_add_u32_e32 v232, 18, v91
	v_mul_hi_i32_i24_e32 v233, 0x3000, v232
	v_mul_i32_i24_e32 v232, 0x3000, v232
	v_lshl_add_u64 v[162:163], s[4:5], 0, v[232:233]
	v_lshl_add_u64 v[232:233], v[162:163], 0, s[8:9]
	v_lshl_add_u64 v[154:155], v[232:233], 0, v[234:235]
	global_load_dwordx4 v[236:239], v[154:155], off
	v_add_u32_e32 v162, 18, v91
	v_mul_hi_i32_i24_e32 v163, 0x3000, v162
	v_mul_i32_i24_e32 v162, 0x3000, v162
	v_lshl_add_u64 v[154:155], s[4:5], 0, v[162:163]
	v_lshl_add_u64 v[154:155], v[154:155], 0, v[8:9]
	global_load_dwordx4 v[232:235], v[154:155], off offset:2048
	global_load_dwordx4 v[244:247], v[24:25], off
	v_mov_b32_e32 v248, v34
	v_mov_b32_e32 v249, v9
	v_add_u32_e32 v242, 18, v91
	v_mul_hi_i32_i24_e32 v243, 0x3000, v242
	v_mul_i32_i24_e32 v242, 0x3000, v242
	v_lshl_add_u64 v[162:163], s[4:5], 0, v[242:243]
	v_lshl_add_u64 v[242:243], v[162:163], 0, s[8:9]
	v_lshl_add_u64 v[154:155], v[242:243], 0, v[248:249]
	global_load_dwordx4 v[252:255], v[154:155], off
	v_add_u32_e32 v162, 18, v91
	v_mul_hi_i32_i24_e32 v163, 0x3000, v162
	v_mul_i32_i24_e32 v162, 0x3000, v162
	v_lshl_add_u64 v[154:155], s[4:5], 0, v[162:163]
	v_lshl_add_u64 v[154:155], v[154:155], 0, v[8:9]
	global_load_dwordx4 v[248:251], v[154:155], off offset:3072
	v_lshl_add_u64 v[66:67], v[54:55], 0, s[10:11]
	v_lshl_add_u64 v[54:55], v[66:67], 0, v[8:9]
	global_load_dwordx4 v[46:49], v[28:29], off offset:-2048
	global_load_dwordx4 v[50:53], v[28:29], off offset:-1024
	v_mov_b32_e32 v31, v9
	v_lshl_add_u64 v[62:63], v[66:67], 0, v[30:31]
	v_lshl_add_u64 v[26:27], v[26:27], 0, s[12:13]
	s_waitcnt vmcnt(27)
	v_and_b32_e32 v65, 0xffff0000, v36
	s_waitcnt vmcnt(26)
	v_and_b32_e32 v71, 0xffff0000, v38
	v_lshlrev_b32_e32 v64, 16, v36
	v_lshlrev_b32_e32 v68, 16, v37
	v_and_b32_e32 v69, 0xffff0000, v37
	v_lshlrev_b32_e32 v70, 16, v38
	v_lshlrev_b32_e32 v72, 16, v39
	v_and_b32_e32 v73, 0xffff0000, v39
	s_waitcnt vmcnt(25)
	v_and_b32_e32 v75, 0xffff0000, v58
	s_waitcnt vmcnt(24)
	v_lshlrev_b32_e32 v36, 16, v60
	v_and_b32_e32 v37, 0xffff0000, v60
	v_lshlrev_b32_e32 v38, 16, v61
	v_and_b32_e32 v39, 0xffff0000, v61
	v_mov_b32_e32 v60, v65
	v_mov_b32_e32 v61, v71
	v_lshlrev_b32_e32 v74, 16, v58
	v_lshlrev_b32_e32 v76, 16, v59
	v_and_b32_e32 v77, 0xffff0000, v59
	v_mov_b32_e32 v58, v64
	v_mov_b32_e32 v59, v70
	v_mov_b32_e32 v84, v75
	v_mov_b32_e32 v85, v37
	v_pk_mul_f32 v[60:61], v[60:61], v[60:61]
	v_mov_b32_e32 v78, v68
	v_mov_b32_e32 v79, v72
	v_mov_b32_e32 v82, v74
	v_mov_b32_e32 v83, v36
	v_pk_mul_f32 v[84:85], v[84:85], v[84:85]
	v_pk_fma_f32 v[58:59], v[58:59], v[58:59], v[60:61]
	v_mov_b32_e32 v80, v69
	v_mov_b32_e32 v81, v73
	v_mov_b32_e32 v86, v76
	v_mov_b32_e32 v87, v38
	v_pk_fma_f32 v[60:61], v[82:83], v[82:83], v[84:85]
	v_pk_fma_f32 v[58:59], v[78:79], v[78:79], v[58:59]
	v_mov_b32_e32 v88, v77
	v_mov_b32_e32 v89, v39
	v_pk_fma_f32 v[60:61], v[86:87], v[86:87], v[60:61]
	v_pk_fma_f32 v[58:59], v[80:81], v[80:81], v[58:59]
	v_pk_fma_f32 v[60:61], v[88:89], v[88:89], v[60:61]
	v_add_f32_e32 v33, v58, v59
	v_add_f32_e32 v33, v33, v60
	v_add_f32_e32 v33, v33, v61
	ds_bpermute_b32 v35, v7, v33
	s_waitcnt lgkmcnt(0)
	v_add_f32_e32 v33, v33, v35
	ds_bpermute_b32 v35, v40, v33
	s_waitcnt lgkmcnt(0)
	v_add_f32_e32 v33, v33, v35
	ds_bpermute_b32 v35, v41, v33
	s_waitcnt lgkmcnt(0)
	v_add_f32_e32 v33, v33, v35
	ds_bpermute_b32 v35, v42, v33
	s_waitcnt lgkmcnt(0)
	v_add_f32_e32 v33, v33, v35
	ds_bpermute_b32 v35, v43, v33
	s_waitcnt lgkmcnt(0)
	v_add_f32_e32 v33, v33, v35
	ds_bpermute_b32 v35, v44, v33
	s_waitcnt lgkmcnt(0)
	v_add_f32_e32 v33, v33, v35
	v_fmamk_f32 v33, v33, 0x3a800000, v45
	v_mul_f32_e32 v35, 0x4b800000, v33
	v_cmp_gt_f32_e64 s[0:1], s24, v33
	s_nop 1
	v_cndmask_b32_e64 v33, v33, v35, s[0:1]
	v_rsq_f32_e32 v33, v33
	s_nop 0
	v_mul_f32_e32 v35, 0x45800000, v33
	v_cndmask_b32_e64 v78, v33, v35, s[0:1]
	v_pk_mul_f32 v[58:59], v[78:79], v[64:65] op_sel_hi:[0,1]
	v_pk_mul_f32 v[60:61], v[78:79], v[68:69] op_sel_hi:[0,1]
	s_waitcnt vmcnt(23)
	v_pk_mul_f32 v[0:1], v[0:1], v[58:59]
	v_pk_mul_f32 v[2:3], v[2:3], v[60:61]
	s_waitcnt vmcnt(1)
	v_pk_fma_f32 v[46:47], v[148:149], v[0:1], v[46:47]
	v_pk_fma_f32 v[48:49], v[150:151], v[2:3], v[48:49]
	global_store_dwordx4 v[28:29], v[46:49], off offset:-2048
	v_pk_mul_f32 v[64:65], v[78:79], v[70:71] op_sel_hi:[0,1]
	v_pk_mul_f32 v[68:69], v[78:79], v[72:73] op_sel_hi:[0,1]
	v_mov_b32_e32 v33, v9
	v_lshl_add_u64 v[62:63], v[66:67], 0, v[32:33]
	v_pk_mul_f32 v[70:71], v[78:79], v[76:77] op_sel_hi:[0,1]
	v_mov_b32_e32 v35, v9
	v_lshl_add_u64 v[66:67], v[66:67], 0, v[34:35]
	v_pk_mul_f32 v[36:37], v[78:79], v[36:37] op_sel_hi:[0,1]
	v_pk_mul_f32 v[38:39], v[78:79], v[38:39] op_sel_hi:[0,1]
	v_mov_b32_e32 v76, v46
	v_mov_b32_e32 v80, v48
	v_mov_b32_e32 v82, v49
	v_pk_mul_f32 v[0:1], v[64:65], v[144:145]
	v_pk_mul_f32 v[2:3], v[68:69], v[146:147]
	s_waitcnt vmcnt(1)
	v_pk_fma_f32 v[50:51], v[164:165], v[0:1], v[50:51]
	v_pk_fma_f32 v[52:53], v[166:167], v[2:3], v[52:53]
	global_store_dwordx4 v[28:29], v[50:53], off offset:-1024
	v_pk_mul_f32 v[68:69], v[78:79], v[74:75] op_sel_hi:[0,1]
	v_mov_b32_e32 v78, v47
	v_mov_b32_e32 v79, v51
	v_mov_b32_e32 v77, v50
	v_pk_mul_f32 v[78:79], v[78:79], v[78:79]
	v_mov_b32_e32 v81, v52
	v_pk_fma_f32 v[76:77], v[76:77], v[76:77], v[78:79]
	v_mov_b32_e32 v83, v53
	v_pk_fma_f32 v[76:77], v[80:81], v[80:81], v[76:77]
	v_pk_mul_f32 v[0:1], v[68:69], v[168:169]
	v_pk_mul_f32 v[2:3], v[70:71], v[170:171]
	v_pk_fma_f32 v[0:1], v[192:193], v[0:1], v[156:157]
	v_pk_fma_f32 v[2:3], v[194:195], v[2:3], v[158:159]
	global_store_dwordx4 v[28:29], v[0:3], off
	v_mov_b32_e32 v68, s22
	v_mov_b32_e32 v69, s20
	v_mov_b32_e32 v70, s21
	v_mov_b32_e32 v71, s19
	v_cndmask_b32_e32 v67, 0, v5, vcc
	v_cndmask_b32_e32 v66, v90, v4, vcc
	v_cndmask_b32_e32 v69, v68, v69, vcc
	v_cndmask_b32_e32 v68, v70, v71, vcc
	v_add_u32_e32 v70, 18, v91
	v_lshlrev_b64 v[66:67], 11, v[66:67]
	v_mul_hi_i32_i24_e32 v71, 0x3000, v70
	v_mul_i32_i24_e32 v70, 0x3000, v70
	v_lshl_add_u64 v[66:67], v[68:69], 0, v[66:67]
	v_lshl_add_u64 v[68:69], s[4:5], 0, v[70:71]
	v_lshl_add_u64 v[70:71], v[68:69], 0, s[8:9]
	v_lshl_add_u64 v[68:69], v[68:69], 0, v[8:9]
	v_lshl_add_u64 v[72:73], v[70:71], 0, v[8:9]
	v_lshlrev_b32_e32 v8, 1, v6
	v_pk_fma_f32 v[76:77], v[82:83], v[82:83], v[76:77]
	v_mov_b32_e32 v78, v1
	v_lshl_add_u64 v[66:67], v[66:67], 0, v[8:9]
	v_add_f32_e32 v8, v76, v77
	v_mov_b32_e32 v76, v0
	v_mov_b32_e32 v80, v2
	v_lshl_add_u64 v[74:75], v[70:71], 0, v[30:31]
	v_lshl_add_u64 v[4:5], v[4:5], 0, s[6:7]
	v_pk_mul_f32 v[36:37], v[36:37], v[196:197]
	v_pk_mul_f32 v[38:39], v[38:39], v[198:199]
	v_pk_fma_f32 v[36:37], v[200:201], v[36:37], v[188:189]
	v_pk_fma_f32 v[38:39], v[202:203], v[38:39], v[190:191]
	global_store_dwordx4 v[28:29], v[36:39], off offset:1024
	v_mov_b32_e32 v79, v37
	v_mov_b32_e32 v77, v36
	v_pk_mul_f32 v[78:79], v[78:79], v[78:79]
	v_mov_b32_e32 v81, v38
	v_pk_fma_f32 v[76:77], v[76:77], v[76:77], v[78:79]
	v_mov_b32_e32 v72, v3
	v_mov_b32_e32 v73, v39
	v_pk_fma_f32 v[76:77], v[80:81], v[80:81], v[76:77]
	v_lshl_add_u64 v[28:29], v[28:29], 0, s[14:15]
	v_pk_fma_f32 v[72:73], v[72:73], v[72:73], v[76:77]
	s_nop 0
	v_add_f32_e32 v8, v8, v72
	v_add_f32_e32 v8, v8, v73
	ds_bpermute_b32 v31, v7, v8
	s_waitcnt lgkmcnt(0)
	v_add_f32_e32 v8, v8, v31
	ds_bpermute_b32 v31, v40, v8
	s_waitcnt lgkmcnt(0)
	v_add_f32_e32 v8, v8, v31
	ds_bpermute_b32 v31, v41, v8
	s_waitcnt lgkmcnt(0)
	v_add_f32_e32 v8, v8, v31
	ds_bpermute_b32 v31, v42, v8
	s_waitcnt lgkmcnt(0)
	v_add_f32_e32 v8, v8, v31
	ds_bpermute_b32 v31, v43, v8
	s_waitcnt lgkmcnt(0)
	v_add_f32_e32 v8, v8, v31
	ds_bpermute_b32 v31, v44, v8
	s_waitcnt lgkmcnt(0)
	v_add_f32_e32 v8, v8, v31
	v_fmamk_f32 v8, v8, 0x3a800000, v45
	v_mul_f32_e32 v31, 0x4b800000, v8
	v_cmp_gt_f32_e32 vcc, s24, v8
	s_nop 1
	v_cndmask_b32_e32 v8, v8, v31, vcc
	v_rsq_f32_e32 v8, v8
	s_nop 0
	v_mul_f32_e32 v31, 0x45800000, v8
	v_cndmask_b32_e32 v8, v8, v31, vcc
	v_pk_mul_f32 v[46:47], v[46:47], v[8:9] op_sel_hi:[1,0]
	v_pk_mul_f32 v[48:49], v[48:49], v[8:9] op_sel_hi:[1,0]
	v_pk_mul_f32 v[50:51], v[50:51], v[8:9] op_sel_hi:[1,0]
	v_pk_mul_f32 v[52:53], v[52:53], v[8:9] op_sel_hi:[1,0]
	v_pk_mul_f32 v[0:1], v[0:1], v[8:9] op_sel_hi:[1,0]
	v_pk_mul_f32 v[2:3], v[2:3], v[8:9] op_sel_hi:[1,0]
	v_pk_mul_f32 v[36:37], v[36:37], v[8:9] op_sel_hi:[1,0]
	v_pk_mul_f32 v[38:39], v[38:39], v[8:9] op_sel_hi:[1,0]
	v_cmp_lt_i32_e32 vcc, s25, v4
	s_or_b64 s[16:17], vcc, s[16:17]
	v_pk_mul_f32 v[46:47], v[204:205], v[46:47]
	v_pk_add_f32 v[54:55], v[212:213], 1.0 op_sel_hi:[1,0]
	v_pk_mul_f32 v[48:49], v[48:49], v[206:207]
	v_pk_add_f32 v[56:57], v[214:215], 1.0 op_sel_hi:[1,0]
	v_pk_fma_f32 v[46:47], v[54:55], v[46:47], v[208:209]
	v_pk_fma_f32 v[48:49], v[56:57], v[48:49], v[210:211]
	v_cvt_pk_bf16_f32 v46, v46, v47
	v_cvt_pk_bf16_f32 v47, v48, v49
	global_store_dwordx2 v[66:67], v[46:47], off
	s_nop 0
	v_lshl_add_u64 v[62:63], v[70:71], 0, v[32:33]
	v_pk_mul_f32 v[46:47], v[50:51], v[216:217]
	v_pk_add_f32 v[50:51], v[224:225], 1.0 op_sel_hi:[1,0]
	v_pk_mul_f32 v[48:49], v[52:53], v[218:219]
	v_pk_add_f32 v[52:53], v[226:227], 1.0 op_sel_hi:[1,0]
	v_pk_fma_f32 v[46:47], v[50:51], v[46:47], v[220:221]
	v_pk_fma_f32 v[48:49], v[52:53], v[48:49], v[222:223]
	v_cvt_pk_bf16_f32 v46, v46, v47
	v_cvt_pk_bf16_f32 v47, v48, v49
	global_store_dwordx2 v[66:67], v[46:47], off offset:512
	s_nop 0
	v_lshl_add_u64 v[58:59], v[70:71], 0, v[34:35]
	v_pk_mul_f32 v[0:1], v[0:1], v[228:229]
	v_pk_add_f32 v[46:47], v[236:237], 1.0 op_sel_hi:[1,0]
	v_pk_mul_f32 v[2:3], v[2:3], v[230:231]
	v_pk_add_f32 v[48:49], v[238:239], 1.0 op_sel_hi:[1,0]
	v_pk_fma_f32 v[0:1], v[46:47], v[0:1], v[232:233]
	v_pk_fma_f32 v[2:3], v[48:49], v[2:3], v[234:235]
	v_cvt_pk_bf16_f32 v0, v0, v1
	v_cvt_pk_bf16_f32 v1, v2, v3
	global_store_dwordx2 v[66:67], v[0:1], off offset:1024
	s_nop 0
	v_pk_mul_f32 v[0:1], v[36:37], v[244:245]
	v_pk_add_f32 v[36:37], v[252:253], 1.0 op_sel_hi:[1,0]
	v_pk_mul_f32 v[2:3], v[38:39], v[246:247]
	v_pk_add_f32 v[38:39], v[254:255], 1.0 op_sel_hi:[1,0]
	v_pk_fma_f32 v[0:1], v[36:37], v[0:1], v[248:249]
	v_pk_fma_f32 v[2:3], v[38:39], v[2:3], v[250:251]
	v_cvt_pk_bf16_f32 v0, v0, v1
	v_cvt_pk_bf16_f32 v1, v2, v3
	global_store_dwordx2 v[66:67], v[0:1], off offset:1536
	s_andn2_b64 exec, exec, s[16:17]
	s_cbranch_execnz .LBB0_1208

.LBB0_1573:
	s_cmp_gt_i32 s70, 18
	s_cselect_b64 s[0:1], -1, 0
	s_cmp_lt_i32 s71, 19
	s_cselect_b64 s[2:3], -1, 0
	s_or_b64 s[0:1], s[0:1], s[2:3]
	s_and_b64 vcc, exec, s[0:1]
	s_cbranch_vccnz .LBB0_1596
	v_readlane_b32 s0, v241, 0
	s_lshl_b32 s18, s0, 3
	v_and_b32_e32 v0, 12, v183
	v_add_u32_e32 v0, s18, v0
	s_waitcnt lgkmcnt(0)
	v_and_or_b32 v4, v183, 3, v0
	s_movk_i32 s0, 0x6000
	v_cmp_gt_i32_e32 vcc, s0, v4
	s_and_saveexec_b64 s[2:3], vcc
	s_cbranch_execz .LBB0_1577
	v_mbcnt_lo_u32_b32 v1, -1, 0
	v_mbcnt_hi_u32_b32 v1, -1, v1
	v_and_b32_e32 v3, 64, v1
	v_add_u32_e32 v3, 64, v3
	v_xor_b32_e32 v5, 32, v1
	v_cmp_lt_i32_e32 vcc, v5, v3
	v_readlane_b32 s36, v241, 1
	v_readlane_b32 s40, v241, 5
	v_cndmask_b32_e32 v5, v1, v5, vcc
	v_lshlrev_b32_e32 v7, 2, v5
	v_xor_b32_e32 v5, 16, v1
	v_cmp_lt_i32_e32 vcc, v5, v3
	v_readlane_b32 s41, v241, 6
	s_add_u32 s4, s68, 0x14000000
	v_cndmask_b32_e32 v5, v1, v5, vcc
	v_lshlrev_b32_e32 v40, 2, v5
	v_xor_b32_e32 v5, 8, v1
	v_cmp_lt_i32_e32 vcc, v5, v3
	v_lshlrev_b32_e32 v0, 2, v178
	v_readlane_b32 s42, v241, 7
	v_cndmask_b32_e32 v5, v1, v5, vcc
	v_lshlrev_b32_e32 v41, 2, v5
	v_xor_b32_e32 v5, 4, v1
	v_cmp_lt_i32_e32 vcc, v5, v3
	v_readlane_b32 s43, v241, 8
	v_readlane_b32 s44, v241, 9
	v_cndmask_b32_e32 v5, v1, v5, vcc
	v_lshlrev_b32_e32 v42, 2, v5
	v_xor_b32_e32 v5, 2, v1
	v_cmp_lt_i32_e32 vcc, v5, v3
	v_readlane_b32 s45, v241, 10
	v_readlane_b32 s46, v241, 11
	v_cndmask_b32_e32 v5, v1, v5, vcc
	v_readlane_b32 s47, v241, 12
	v_readlane_b32 s48, v241, 13
	v_readlane_b32 s49, v241, 14
	v_readlane_b32 s50, v241, 15
	v_readlane_b32 s51, v241, 16
	s_mov_b64 s[20:21], s[40:41]
	s_addc_u32 s5, s69, 0
	v_and_b32_e32 v6, 0xfc, v0
	s_lshl_b32 s6, s78, 3
	v_lshlrev_b32_e32 v43, 2, v5
	v_xor_b32_e32 v5, 1, v1
	s_mov_b64 s[22:23], s[42:43]
	v_mov_b32_e32 v9, 0
	v_or_b32_e32 v0, 0x100, v6
	v_or_b32_e32 v2, 0x200, v6
	v_or_b32_e32 v34, 0x300, v6
	v_cmp_lt_i32_e32 vcc, v5, v3
	s_add_u32 s0, s22, 0x2000
	s_addc_u32 s1, s23, 0
	v_cndmask_b32_e32 v1, v1, v5, vcc
	v_lshlrev_b32_e32 v8, 2, v6
	v_lshlrev_b32_e32 v20, 2, v0
	v_mov_b32_e32 v21, v9
	v_lshlrev_b32_e32 v22, 2, v2
	v_mov_b32_e32 v23, v9
	v_lshlrev_b32_e32 v24, 2, v34
	v_mov_b32_e32 v25, v9
	v_ashrrev_i32_e32 v5, 31, v4
	v_lshlrev_b32_e32 v44, 2, v1
	v_lshl_add_u64 v[10:11], s[0:1], 0, v[8:9]
	v_lshl_add_u64 v[12:13], s[0:1], 0, v[20:21]
	v_lshl_add_u64 v[14:15], s[0:1], 0, v[22:23]
	v_lshl_add_u64 v[16:17], s[0:1], 0, v[24:25]
	s_add_u32 s0, s20, 0x3000
	v_and_b32_e32 v1, 63, v178
	v_lshlrev_b64 v[28:29], 12, v[4:5]
	s_addc_u32 s1, s21, 0
	v_lshlrev_b64 v[26:27], 11, v[4:5]
	v_lshl_or_b32 v28, v1, 4, v28
	v_lshl_add_u64 v[18:19], s[0:1], 0, v[8:9]
	v_lshl_add_u64 v[20:21], s[0:1], 0, v[20:21]
	v_lshl_add_u64 v[22:23], s[0:1], 0, v[22:23]
	v_lshl_add_u64 v[24:25], s[0:1], 0, v[24:25]
	s_ashr_i32 s7, s6, 31
	v_lshl_or_b32 v26, v1, 3, v26
	v_lshl_add_u64 v[28:29], s[94:95], 0, v[28:29]
	s_mov_b64 s[0:1], 0x800
	s_mov_b64 s[8:9], 0x2000
	v_lshl_add_u64 v[26:27], s[68:69], 0, v[26:27]
	s_lshl_b64 s[10:11], s[6:7], 11
	v_lshl_add_u64 v[28:29], v[28:29], 0, s[0:1]
	s_lshl_b64 s[12:13], s[6:7], 12
	s_mov_b64 s[14:15], 0
	s_movk_i32 s19, 0x2000
	v_lshlrev_b32_e32 v30, 2, v0
	v_lshlrev_b32_e32 v32, 2, v2
	v_lshlrev_b32_e32 v34, 2, v34
	v_mov_b32_e32 v45, 0x358637bd
	s_mov_b32 s20, 0x800000
	s_mov_b64 s[16:17], 0x1000
	s_movk_i32 s21, 0x5fff
	v_mov_b32_e32 v46, 0xf000000
	v_mov_b32_e32 v47, 0x13000000
	v_readlane_b32 s37, v241, 2
	v_readlane_b32 s38, v241, 3
	v_readlane_b32 s39, v241, 4
	s_mov_b64 s[24:25], s[44:45]
	s_mov_b64 s[26:27], s[46:47]
	s_mov_b64 s[28:29], s[48:49]
	s_mov_b64 s[30:31], s[50:51]
	s_waitcnt vmcnt(0)
.LBB0_1576:
	global_load_dwordx2 v[36:37], v[26:27], off
	global_load_dwordx2 v[38:39], v[26:27], off offset:512
	global_load_dwordx2 v[60:61], v[26:27], off offset:1024
	global_load_dwordx2 v[62:63], v[26:27], off offset:1536
	v_add_u32_e32 v92, 0xffffe000, v4
	v_ashrrev_i32_e32 v33, 11, v92
	v_add_u32_e32 v33, 1, v33
	v_cmp_gt_i32_e32 vcc, s19, v4
	v_lshlrev_b32_e32 v8, 2, v6
	global_load_dwordx4 v[0:3], v[10:11], off
	v_mov_b32_e32 v148, v33
	v_cndmask_b32_e64 v149, v148, 0, vcc
	v_add_u32_e32 v148, 18, v149
	v_mul_hi_i32_i24_e32 v145, 0x3000, v148
	v_mul_i32_i24_e32 v144, 0x3000, v148
	v_lshl_add_u64 v[144:145], s[4:5], 0, v[144:145]
	v_lshl_add_u64 v[146:147], v[144:145], 0, s[8:9]
	v_lshl_add_u64 v[144:145], v[146:147], 0, v[8:9]
	global_load_dwordx4 v[156:159], v[144:145], off
	global_load_dwordx4 v[144:147], v[12:13], off
	v_mov_b32_e32 v160, v33
	v_mov_b32_e32 v162, v30
	v_cndmask_b32_e64 v164, v160, 0, vcc
	v_add_u32_e32 v160, 18, v164
	v_mul_hi_i32_i24_e32 v151, 0x3000, v160
	v_mul_i32_i24_e32 v150, 0x3000, v160
	v_lshl_add_u64 v[150:151], s[4:5], 0, v[150:151]
	v_lshl_add_u64 v[154:155], v[150:151], 0, s[8:9]
	v_mov_b32_e32 v163, v9
	v_lshl_add_u64 v[148:149], v[154:155], 0, v[162:163]
	global_load_dwordx4 v[168:171], v[148:149], off
	global_load_dwordx4 v[148:151], v[28:29], off
	global_load_dwordx4 v[164:167], v[14:15], off
	v_mov_b32_e32 v191, v33
	v_mov_b32_e32 v190, v32
	v_cndmask_b32_e64 v160, v191, 0, vcc
	v_add_u32_e32 v191, 18, v160
	v_mul_hi_i32_i24_e32 v163, 0x3000, v191
	v_mul_i32_i24_e32 v162, 0x3000, v191
	v_lshl_add_u64 v[162:163], s[4:5], 0, v[162:163]
	v_lshl_add_u64 v[188:189], v[162:163], 0, s[8:9]
	v_mov_b32_e32 v191, v9
	v_lshl_add_u64 v[154:155], v[188:189], 0, v[190:191]
	global_load_dwordx4 v[192:195], v[154:155], off
	global_load_dwordx4 v[188:191], v[28:29], off offset:1024
	global_load_dwordx4 v[196:199], v[16:17], off
	v_mov_b32_e32 v160, v33
	v_mov_b32_e32 v200, v34
	v_cndmask_b32_e64 v187, v160, 0, vcc
	v_add_u32_e32 v160, 18, v187
	v_mul_hi_i32_i24_e32 v163, 0x3000, v160
	v_mul_i32_i24_e32 v162, 0x3000, v160
	v_lshl_add_u64 v[162:163], s[4:5], 0, v[162:163]
	v_lshl_add_u64 v[154:155], v[162:163], 0, s[8:9]
	v_mov_b32_e32 v201, v9
	v_lshl_add_u64 v[154:155], v[154:155], 0, v[200:201]
	global_load_dwordx4 v[204:207], v[154:155], off
	global_load_dwordx4 v[200:203], v[18:19], off
	v_cndmask_b32_e64 v160, v33, 0, vcc
	v_add_u32_e32 v208, 27, v160
	v_mul_hi_i32_i24_e32 v209, 0x3000, v208
	v_mul_i32_i24_e32 v208, 0x3000, v208
	v_lshl_add_u64 v[162:163], s[4:5], 0, v[208:209]
	v_lshl_add_u64 v[208:209], v[162:163], 0, s[16:17]
	v_lshl_add_u64 v[154:155], v[208:209], 0, v[8:9]
	global_load_dwordx4 v[212:215], v[154:155], off
	v_cndmask_b32_e64 v160, v33, 0, vcc
	v_add_u32_e32 v162, 27, v160
	v_mul_hi_i32_i24_e32 v163, 0x3000, v162
	v_mul_i32_i24_e32 v162, 0x3000, v162
	v_lshl_add_u64 v[154:155], s[4:5], 0, v[162:163]
	v_lshl_add_u64 v[154:155], v[154:155], 0, v[8:9]
	global_load_dwordx4 v[208:211], v[154:155], off
	global_load_dwordx4 v[216:219], v[20:21], off
	v_mov_b32_e32 v222, v30
	v_cndmask_b32_e64 v160, v33, 0, vcc
	v_mov_b32_e32 v223, v9
	v_add_u32_e32 v220, 27, v160
	v_mul_hi_i32_i24_e32 v221, 0x3000, v220
	v_mul_i32_i24_e32 v220, 0x3000, v220
	v_lshl_add_u64 v[162:163], s[4:5], 0, v[220:221]
	v_lshl_add_u64 v[220:221], v[162:163], 0, s[16:17]
	v_lshl_add_u64 v[154:155], v[220:221], 0, v[222:223]
	global_load_dwordx4 v[224:227], v[154:155], off
	v_cndmask_b32_e64 v160, v33, 0, vcc
	v_add_u32_e32 v162, 27, v160
	v_mul_hi_i32_i24_e32 v163, 0x3000, v162
	v_mul_i32_i24_e32 v162, 0x3000, v162
	v_lshl_add_u64 v[154:155], s[4:5], 0, v[162:163]
	v_lshl_add_u64 v[154:155], v[154:155], 0, v[8:9]
	global_load_dwordx4 v[220:223], v[154:155], off offset:1024
	global_load_dwordx4 v[228:231], v[22:23], off
	v_mov_b32_e32 v235, v33
	v_mov_b32_e32 v234, v32
	v_cndmask_b32_e64 v160, v235, 0, vcc
	v_mov_b32_e32 v235, v9
	v_add_u32_e32 v232, 27, v160
	v_mul_hi_i32_i24_e32 v233, 0x3000, v232
	v_mul_i32_i24_e32 v232, 0x3000, v232
	v_lshl_add_u64 v[162:163], s[4:5], 0, v[232:233]
	v_lshl_add_u64 v[232:233], v[162:163], 0, s[16:17]
	v_lshl_add_u64 v[154:155], v[232:233], 0, v[234:235]
	global_load_dwordx4 v[236:239], v[154:155], off
	v_cndmask_b32_e64 v160, v33, 0, vcc
	v_add_u32_e32 v162, 27, v160
	v_mul_hi_i32_i24_e32 v163, 0x3000, v162
	v_mul_i32_i24_e32 v162, 0x3000, v162
	v_lshl_add_u64 v[154:155], s[4:5], 0, v[162:163]
	v_lshl_add_u64 v[154:155], v[154:155], 0, v[8:9]
	global_load_dwordx4 v[232:235], v[154:155], off offset:2048
	global_load_dwordx4 v[244:247], v[24:25], off
	v_mov_b32_e32 v248, v34
	v_cndmask_b32_e64 v160, v33, 0, vcc
	v_mov_b32_e32 v249, v9
	v_add_u32_e32 v242, 27, v160
	v_mul_hi_i32_i24_e32 v243, 0x3000, v242
	v_mul_i32_i24_e32 v242, 0x3000, v242
	v_lshl_add_u64 v[162:163], s[4:5], 0, v[242:243]
	v_lshl_add_u64 v[242:243], v[162:163], 0, s[16:17]
	v_lshl_add_u64 v[154:155], v[242:243], 0, v[248:249]
	global_load_dwordx4 v[252:255], v[154:155], off
	v_cndmask_b32_e64 v160, v33, 0, vcc
	v_add_u32_e32 v162, 27, v160
	v_mul_hi_i32_i24_e32 v163, 0x3000, v162
	v_mul_i32_i24_e32 v162, 0x3000, v162
	v_lshl_add_u64 v[154:155], s[4:5], 0, v[162:163]
	v_lshl_add_u64 v[154:155], v[154:155], 0, v[8:9]
	global_load_dwordx4 v[248:251], v[154:155], off offset:3072
	v_cndmask_b32_e64 v93, v33, 0, vcc
	v_add_u32_e32 v33, 18, v93
	v_mul_hi_i32_i24_e32 v57, 0x3000, v33
	v_mul_i32_i24_e32 v56, 0x3000, v33
	v_lshl_add_u64 v[56:57], s[4:5], 0, v[56:57]
	v_lshl_add_u64 v[68:69], v[56:57], 0, s[8:9]
	v_lshl_add_u64 v[56:57], v[68:69], 0, v[8:9]
	global_load_dwordx4 v[48:51], v[28:29], off offset:-2048
	global_load_dwordx4 v[52:55], v[28:29], off offset:-1024
	v_mov_b32_e32 v31, v9
	v_lshl_add_u64 v[64:65], v[68:69], 0, v[30:31]
	v_lshl_add_u64 v[26:27], v[26:27], 0, s[10:11]
	s_waitcnt vmcnt(27)
	v_and_b32_e32 v67, 0xffff0000, v36
	s_waitcnt vmcnt(26)
	v_and_b32_e32 v73, 0xffff0000, v38
	v_lshlrev_b32_e32 v66, 16, v36
	v_lshlrev_b32_e32 v70, 16, v37
	v_and_b32_e32 v71, 0xffff0000, v37
	v_lshlrev_b32_e32 v72, 16, v38
	v_lshlrev_b32_e32 v74, 16, v39
	v_and_b32_e32 v75, 0xffff0000, v39
	s_waitcnt vmcnt(25)
	v_and_b32_e32 v77, 0xffff0000, v60
	s_waitcnt vmcnt(24)
	v_lshlrev_b32_e32 v36, 16, v62
	v_and_b32_e32 v37, 0xffff0000, v62
	v_lshlrev_b32_e32 v38, 16, v63
	v_and_b32_e32 v39, 0xffff0000, v63
	v_mov_b32_e32 v62, v67
	v_mov_b32_e32 v63, v73
	v_lshlrev_b32_e32 v76, 16, v60
	v_lshlrev_b32_e32 v78, 16, v61
	v_and_b32_e32 v79, 0xffff0000, v61
	v_mov_b32_e32 v60, v66
	v_mov_b32_e32 v61, v72
	v_mov_b32_e32 v86, v77
	v_mov_b32_e32 v87, v37
	v_pk_mul_f32 v[62:63], v[62:63], v[62:63]
	v_mov_b32_e32 v80, v70
	v_mov_b32_e32 v81, v74
	v_mov_b32_e32 v84, v76
	v_mov_b32_e32 v85, v36
	v_pk_mul_f32 v[86:87], v[86:87], v[86:87]
	v_pk_fma_f32 v[60:61], v[60:61], v[60:61], v[62:63]
	v_mov_b32_e32 v82, v71
	v_mov_b32_e32 v83, v75
	v_mov_b32_e32 v88, v78
	v_mov_b32_e32 v89, v38
	v_pk_fma_f32 v[62:63], v[84:85], v[84:85], v[86:87]
	v_pk_fma_f32 v[60:61], v[80:81], v[80:81], v[60:61]
	v_mov_b32_e32 v90, v79
	v_mov_b32_e32 v91, v39
	v_pk_fma_f32 v[62:63], v[88:89], v[88:89], v[62:63]
	v_pk_fma_f32 v[60:61], v[82:83], v[82:83], v[60:61]
	v_pk_fma_f32 v[62:63], v[90:91], v[90:91], v[62:63]
	v_add_f32_e32 v33, v60, v61
	v_add_f32_e32 v33, v33, v62
	v_add_f32_e32 v33, v33, v63
	ds_bpermute_b32 v35, v7, v33
	s_waitcnt lgkmcnt(0)
	v_add_f32_e32 v33, v33, v35
	ds_bpermute_b32 v35, v40, v33
	s_waitcnt lgkmcnt(0)
	v_add_f32_e32 v33, v33, v35
	ds_bpermute_b32 v35, v41, v33
	s_waitcnt lgkmcnt(0)
	v_add_f32_e32 v33, v33, v35
	ds_bpermute_b32 v35, v42, v33
	s_waitcnt lgkmcnt(0)
	v_add_f32_e32 v33, v33, v35
	ds_bpermute_b32 v35, v43, v33
	s_waitcnt lgkmcnt(0)
	v_add_f32_e32 v33, v33, v35
	ds_bpermute_b32 v35, v44, v33
	s_waitcnt lgkmcnt(0)
	v_add_f32_e32 v33, v33, v35
	v_fmamk_f32 v33, v33, 0x3a800000, v45
	v_mul_f32_e32 v35, 0x4b800000, v33
	v_cmp_gt_f32_e64 s[0:1], s20, v33
	s_nop 1
	v_cndmask_b32_e64 v33, v33, v35, s[0:1]
	v_rsq_f32_e32 v33, v33
	s_nop 0
	v_mul_f32_e32 v35, 0x45800000, v33
	v_cndmask_b32_e64 v80, v33, v35, s[0:1]
	v_pk_mul_f32 v[60:61], v[80:81], v[66:67] op_sel_hi:[0,1]
	v_pk_mul_f32 v[62:63], v[80:81], v[70:71] op_sel_hi:[0,1]
	s_waitcnt vmcnt(23)
	v_pk_mul_f32 v[0:1], v[0:1], v[60:61]
	v_pk_mul_f32 v[2:3], v[2:3], v[62:63]
	s_waitcnt vmcnt(1)
	v_pk_fma_f32 v[48:49], v[156:157], v[0:1], v[48:49]
	v_pk_fma_f32 v[50:51], v[158:159], v[2:3], v[50:51]
	global_store_dwordx4 v[28:29], v[48:51], off offset:-2048
	v_pk_mul_f32 v[66:67], v[80:81], v[72:73] op_sel_hi:[0,1]
	v_pk_mul_f32 v[70:71], v[80:81], v[74:75] op_sel_hi:[0,1]
	v_mov_b32_e32 v33, v9
	v_lshl_add_u64 v[64:65], v[68:69], 0, v[32:33]
	v_pk_mul_f32 v[72:73], v[80:81], v[78:79] op_sel_hi:[0,1]
	v_mov_b32_e32 v35, v9
	v_lshl_add_u64 v[68:69], v[68:69], 0, v[34:35]
	v_pk_mul_f32 v[36:37], v[80:81], v[36:37] op_sel_hi:[0,1]
	v_pk_mul_f32 v[38:39], v[80:81], v[38:39] op_sel_hi:[0,1]
	v_mov_b32_e32 v78, v48
	v_mov_b32_e32 v82, v50
	v_mov_b32_e32 v84, v51
	v_pk_mul_f32 v[0:1], v[66:67], v[144:145]
	v_pk_mul_f32 v[2:3], v[70:71], v[146:147]
	s_waitcnt vmcnt(1)
	v_pk_fma_f32 v[52:53], v[168:169], v[0:1], v[52:53]
	v_pk_fma_f32 v[54:55], v[170:171], v[2:3], v[54:55]
	global_store_dwordx4 v[28:29], v[52:55], off offset:-1024
	v_pk_mul_f32 v[70:71], v[80:81], v[76:77] op_sel_hi:[0,1]
	v_mov_b32_e32 v80, v49
	v_mov_b32_e32 v81, v53
	v_mov_b32_e32 v79, v52
	v_pk_mul_f32 v[80:81], v[80:81], v[80:81]
	v_mov_b32_e32 v83, v54
	v_pk_fma_f32 v[78:79], v[78:79], v[78:79], v[80:81]
	v_mov_b32_e32 v85, v55
	v_pk_fma_f32 v[78:79], v[82:83], v[82:83], v[78:79]
	v_pk_mul_f32 v[0:1], v[70:71], v[164:165]
	v_pk_mul_f32 v[2:3], v[72:73], v[166:167]
	v_pk_fma_f32 v[0:1], v[192:193], v[0:1], v[148:149]
	v_pk_fma_f32 v[2:3], v[194:195], v[2:3], v[150:151]
	global_store_dwordx4 v[28:29], v[0:3], off
	v_mov_b32_e32 v69, v9
	v_cndmask_b32_e32 v71, 0, v5, vcc
	v_cndmask_b32_e32 v70, v92, v4, vcc
	v_cndmask_b32_e32 v68, v46, v47, vcc
	v_add_u32_e32 v72, 27, v93
	v_lshl_add_u64 v[68:69], s[68:69], 0, v[68:69]
	v_lshlrev_b64 v[70:71], 11, v[70:71]
	v_mul_hi_i32_i24_e32 v73, 0x3000, v72
	v_mul_i32_i24_e32 v72, 0x3000, v72
	v_lshl_add_u64 v[68:69], v[68:69], 0, v[70:71]
	v_lshl_add_u64 v[70:71], s[4:5], 0, v[72:73]
	v_lshl_add_u64 v[72:73], v[70:71], 0, s[16:17]
	v_lshl_add_u64 v[70:71], v[70:71], 0, v[8:9]
	v_lshl_add_u64 v[74:75], v[72:73], 0, v[8:9]
	v_lshlrev_b32_e32 v8, 1, v6
	v_pk_fma_f32 v[78:79], v[84:85], v[84:85], v[78:79]
	v_mov_b32_e32 v80, v1
	v_lshl_add_u64 v[68:69], v[68:69], 0, v[8:9]
	v_add_f32_e32 v8, v78, v79
	v_mov_b32_e32 v78, v0
	v_mov_b32_e32 v82, v2
	v_lshl_add_u64 v[76:77], v[72:73], 0, v[30:31]
	v_lshl_add_u64 v[4:5], v[4:5], 0, s[6:7]
	v_pk_mul_f32 v[36:37], v[36:37], v[196:197]
	v_pk_mul_f32 v[38:39], v[38:39], v[198:199]
	v_pk_fma_f32 v[36:37], v[204:205], v[36:37], v[188:189]
	v_pk_fma_f32 v[38:39], v[206:207], v[38:39], v[190:191]
	global_store_dwordx4 v[28:29], v[36:39], off offset:1024
	v_mov_b32_e32 v81, v37
	v_mov_b32_e32 v79, v36
	v_pk_mul_f32 v[80:81], v[80:81], v[80:81]
	v_mov_b32_e32 v83, v38
	v_pk_fma_f32 v[78:79], v[78:79], v[78:79], v[80:81]
	v_mov_b32_e32 v74, v3
	v_mov_b32_e32 v75, v39
	v_pk_fma_f32 v[78:79], v[82:83], v[82:83], v[78:79]
	v_lshl_add_u64 v[28:29], v[28:29], 0, s[12:13]
	v_pk_fma_f32 v[74:75], v[74:75], v[74:75], v[78:79]
	s_nop 0
	v_add_f32_e32 v8, v8, v74
	v_add_f32_e32 v8, v8, v75
	ds_bpermute_b32 v31, v7, v8
	s_waitcnt lgkmcnt(0)
	v_add_f32_e32 v8, v8, v31
	ds_bpermute_b32 v31, v40, v8
	s_waitcnt lgkmcnt(0)
	v_add_f32_e32 v8, v8, v31
	ds_bpermute_b32 v31, v41, v8
	s_waitcnt lgkmcnt(0)
	v_add_f32_e32 v8, v8, v31
	ds_bpermute_b32 v31, v42, v8
	s_waitcnt lgkmcnt(0)
	v_add_f32_e32 v8, v8, v31
	ds_bpermute_b32 v31, v43, v8
	s_waitcnt lgkmcnt(0)
	v_add_f32_e32 v8, v8, v31
	ds_bpermute_b32 v31, v44, v8
	s_waitcnt lgkmcnt(0)
	v_add_f32_e32 v8, v8, v31
	v_fmamk_f32 v8, v8, 0x3a800000, v45
	v_mul_f32_e32 v31, 0x4b800000, v8
	v_cmp_gt_f32_e32 vcc, s20, v8
	s_nop 1
	v_cndmask_b32_e32 v8, v8, v31, vcc
	v_rsq_f32_e32 v8, v8
	s_nop 0
	v_mul_f32_e32 v31, 0x45800000, v8
	v_cndmask_b32_e32 v8, v8, v31, vcc
	v_pk_mul_f32 v[48:49], v[48:49], v[8:9] op_sel_hi:[1,0]
	v_pk_mul_f32 v[50:51], v[50:51], v[8:9] op_sel_hi:[1,0]
	v_pk_mul_f32 v[52:53], v[52:53], v[8:9] op_sel_hi:[1,0]
	v_pk_mul_f32 v[54:55], v[54:55], v[8:9] op_sel_hi:[1,0]
	v_pk_mul_f32 v[0:1], v[0:1], v[8:9] op_sel_hi:[1,0]
	v_pk_mul_f32 v[2:3], v[2:3], v[8:9] op_sel_hi:[1,0]
	v_pk_mul_f32 v[36:37], v[36:37], v[8:9] op_sel_hi:[1,0]
	v_pk_mul_f32 v[38:39], v[38:39], v[8:9] op_sel_hi:[1,0]
	v_cmp_lt_i32_e32 vcc, s21, v4
	s_or_b64 s[14:15], vcc, s[14:15]
	v_pk_mul_f32 v[48:49], v[200:201], v[48:49]
	v_pk_add_f32 v[56:57], v[212:213], 1.0 op_sel_hi:[1,0]
	v_pk_mul_f32 v[50:51], v[50:51], v[202:203]
	v_pk_add_f32 v[58:59], v[214:215], 1.0 op_sel_hi:[1,0]
	v_pk_fma_f32 v[48:49], v[56:57], v[48:49], v[208:209]
	v_pk_fma_f32 v[50:51], v[58:59], v[50:51], v[210:211]
	v_cvt_pk_bf16_f32 v48, v48, v49
	v_cvt_pk_bf16_f32 v49, v50, v51
	global_store_dwordx2 v[68:69], v[48:49], off
	s_nop 0
	v_lshl_add_u64 v[64:65], v[72:73], 0, v[32:33]
	v_pk_mul_f32 v[48:49], v[52:53], v[216:217]
	v_pk_add_f32 v[52:53], v[224:225], 1.0 op_sel_hi:[1,0]
	v_pk_mul_f32 v[50:51], v[54:55], v[218:219]
	v_pk_add_f32 v[54:55], v[226:227], 1.0 op_sel_hi:[1,0]
	v_pk_fma_f32 v[48:49], v[52:53], v[48:49], v[220:221]
	v_pk_fma_f32 v[50:51], v[54:55], v[50:51], v[222:223]
	v_cvt_pk_bf16_f32 v48, v48, v49
	v_cvt_pk_bf16_f32 v49, v50, v51
	global_store_dwordx2 v[68:69], v[48:49], off offset:512
	s_nop 0
	v_lshl_add_u64 v[60:61], v[72:73], 0, v[34:35]
	v_pk_mul_f32 v[0:1], v[0:1], v[228:229]
	v_pk_add_f32 v[48:49], v[236:237], 1.0 op_sel_hi:[1,0]
	v_pk_mul_f32 v[2:3], v[2:3], v[230:231]
	v_pk_add_f32 v[50:51], v[238:239], 1.0 op_sel_hi:[1,0]
	v_pk_fma_f32 v[0:1], v[48:49], v[0:1], v[232:233]
	v_pk_fma_f32 v[2:3], v[50:51], v[2:3], v[234:235]
	v_cvt_pk_bf16_f32 v0, v0, v1
	v_cvt_pk_bf16_f32 v1, v2, v3
	global_store_dwordx2 v[68:69], v[0:1], off offset:1024
	s_nop 0
	v_pk_mul_f32 v[0:1], v[36:37], v[244:245]
	v_pk_add_f32 v[36:37], v[252:253], 1.0 op_sel_hi:[1,0]
	v_pk_mul_f32 v[2:3], v[38:39], v[246:247]
	v_pk_add_f32 v[38:39], v[254:255], 1.0 op_sel_hi:[1,0]
	v_pk_fma_f32 v[0:1], v[36:37], v[0:1], v[248:249]
	v_pk_fma_f32 v[2:3], v[38:39], v[2:3], v[250:251]
	v_cvt_pk_bf16_f32 v0, v0, v1
	v_cvt_pk_bf16_f32 v1, v2, v3
	global_store_dwordx2 v[68:69], v[0:1], off offset:1536
	s_andn2_b64 exec, exec, s[14:15]
	s_cbranch_execnz .LBB0_1576

.LBB0_2293:
	s_cmp_gt_i32 s70, 22
	s_cselect_b64 s[0:1], -1, 0
	s_cmp_lt_i32 s71, 23
	s_cselect_b64 s[2:3], -1, 0
	s_or_b64 s[0:1], s[0:1], s[2:3]
	s_and_b64 vcc, exec, s[0:1]
	s_cbranch_vccnz .LBB0_2309
	v_and_b32_e32 v0, 12, v183
	v_readlane_b32 s0, v241, 0
	s_nop 1
	v_lshl_add_u32 v0, s0, 3, v0
	v_and_or_b32 v0, v183, 3, v0
	s_movk_i32 s0, 0x6000
	v_cmp_gt_i32_e32 vcc, s0, v0
	s_and_saveexec_b64 s[0:1], vcc
	s_cbranch_execz .LBB0_2297
	v_lshlrev_b32_e32 v1, 2, v178
	v_and_b32_e32 v16, 0xfc, v1
	v_mbcnt_lo_u32_b32 v1, -1, 0
	v_mbcnt_hi_u32_b32 v1, -1, v1
	s_waitcnt lgkmcnt(0)
	v_and_b32_e32 v2, 64, v1
	v_add_u32_e32 v2, 64, v2
	v_xor_b32_e32 v4, 32, v1
	v_cmp_lt_i32_e32 vcc, v4, v2
	v_readlane_b32 s4, v241, 1
	v_readlane_b32 s6, v241, 3
	v_cndmask_b32_e32 v4, v1, v4, vcc
	v_lshlrev_b32_e32 v22, 2, v4
	v_xor_b32_e32 v4, 16, v1
	v_cmp_lt_i32_e32 vcc, v4, v2
	v_readlane_b32 s7, v241, 4
	v_readlane_b32 s10, v241, 7
	v_cndmask_b32_e32 v4, v1, v4, vcc
	v_lshlrev_b32_e32 v23, 2, v4
	v_xor_b32_e32 v4, 8, v1
	v_cmp_lt_i32_e32 vcc, v4, v2
	v_readlane_b32 s11, v241, 8
	s_lshl_b32 s2, s78, 3
	v_cndmask_b32_e32 v4, v1, v4, vcc
	v_lshlrev_b32_e32 v24, 2, v4
	v_xor_b32_e32 v4, 4, v1
	v_cmp_lt_i32_e32 vcc, v4, v2
	s_mov_b64 s[6:7], s[10:11]
	v_readlane_b32 s5, v241, 2
	v_cndmask_b32_e32 v4, v1, v4, vcc
	v_lshlrev_b32_e32 v25, 2, v4
	v_xor_b32_e32 v4, 2, v1
	v_cmp_lt_i32_e32 vcc, v4, v2
	s_add_u32 s4, s6, 0x3000
	v_mov_b32_e32 v3, 0
	v_cndmask_b32_e32 v4, v1, v4, vcc
	v_lshlrev_b32_e32 v26, 2, v4
	v_xor_b32_e32 v4, 1, v1
	v_or_b32_e32 v18, 0x100, v16
	v_cmp_lt_i32_e32 vcc, v4, v2
	s_addc_u32 s5, s7, 0
	v_lshlrev_b32_e32 v2, 2, v16
	v_or_b32_e32 v20, 0x200, v16
	v_cndmask_b32_e32 v1, v1, v4, vcc
	v_lshl_add_u64 v[4:5], s[4:5], 0, v[2:3]
	v_lshlrev_b32_e32 v2, 2, v18
	v_or_b32_e32 v28, 0x300, v16
	v_lshl_add_u64 v[6:7], s[4:5], 0, v[2:3]
	v_lshlrev_b32_e32 v2, 2, v20
	v_lshlrev_b32_e32 v27, 2, v1
	v_lshl_add_u64 v[8:9], s[4:5], 0, v[2:3]
	v_lshlrev_b32_e32 v2, 2, v28
	v_ashrrev_i32_e32 v1, 31, v0
	v_lshl_add_u64 v[10:11], s[4:5], 0, v[2:3]
	v_and_b32_e32 v2, 63, v178
	v_lshlrev_b64 v[14:15], 12, v[0:1]
	v_lshlrev_b64 v[12:13], 11, v[0:1]
	v_lshl_or_b32 v14, v2, 4, v14
	v_readlane_b32 s8, v241, 5
	v_readlane_b32 s9, v241, 6
	v_readlane_b32 s12, v241, 9
	v_readlane_b32 s13, v241, 10
	v_lshl_or_b32 v12, v2, 3, v12
	s_ashr_i32 s3, s2, 31
	v_lshl_add_u64 v[14:15], s[94:95], 0, v[14:15]
	s_mov_b64 s[6:7], 0x800
	v_lshl_add_u64 v[12:13], s[68:69], 0, v[12:13]
	s_lshl_b64 s[4:5], s[2:3], 11
	v_lshl_add_u64 v[14:15], v[14:15], 0, s[6:7]
	s_lshl_b64 s[6:7], s[2:3], 12
	s_mov_b64 s[8:9], 0
	s_movk_i32 s3, 0x1fff
	s_mov_b64 s[10:11], 0x14002000
	v_lshlrev_b32_e32 v2, 2, v16
	v_lshlrev_b32_e32 v16, 2, v18
	v_mov_b32_e32 v17, v3
	v_lshlrev_b32_e32 v18, 2, v20
	v_mov_b32_e32 v19, v3
	v_lshlrev_b32_e32 v20, 2, v28
	v_mov_b32_e32 v21, v3
	v_mov_b32_e32 v1, 0x358637bd
	s_mov_b32 s12, 0x800000
	s_movk_i32 s13, 0x5fff
	v_readlane_b32 s14, v241, 11
	v_readlane_b32 s15, v241, 12
	v_readlane_b32 s16, v241, 13
	v_readlane_b32 s17, v241, 14
	v_readlane_b32 s18, v241, 15
	v_readlane_b32 s19, v241, 16
	s_waitcnt vmcnt(0)
.LBB0_2296:
	global_load_dwordx2 v[44:45], v[12:13], off
	global_load_dwordx2 v[46:47], v[12:13], off offset:512
	global_load_dwordx2 v[48:49], v[12:13], off offset:1024
	global_load_dwordx2 v[50:51], v[12:13], off offset:1536
	v_add_u32_e32 v40, 0xffffe000, v0
	v_ashrrev_i32_e32 v40, 11, v40
	v_add_u32_e32 v40, 28, v40
	v_cmp_lt_i32_e32 vcc, s3, v0
	global_load_dwordx4 v[28:31], v[4:5], off
	global_load_dwordx4 v[32:35], v[14:15], off offset:-2048
	global_load_dwordx4 v[36:39], v[14:15], off offset:-1024
	v_cndmask_b32_e32 v40, 27, v40, vcc
	v_mul_hi_i32_i24_e32 v41, 0x3000, v40
	v_mul_i32_i24_e32 v40, 0x3000, v40
	v_lshl_add_u64 v[40:41], s[68:69], 0, v[40:41]
	v_lshl_add_u64 v[52:53], v[40:41], 0, s[10:11]
	v_lshl_add_u64 v[40:41], v[52:53], 0, v[2:3]
	global_load_dwordx4 v[40:43], v[40:41], off
	v_lshl_add_u64 v[54:55], v[52:53], 0, v[16:17]
	v_add_u32_e32 v0, s2, v0
	v_lshl_add_u64 v[12:13], v[12:13], 0, s[4:5]
	global_load_dwordx4 v[144:147], v[6:7], off
	global_load_dwordx4 v[148:151], v[54:55], off
	global_load_dwordx4 v[156:159], v[14:15], off
	global_load_dwordx4 v[164:167], v[8:9], off
	v_lshl_add_u64 v[154:155], v[52:53], 0, v[18:19]
	global_load_dwordx4 v[168:171], v[154:155], off
	global_load_dwordx4 v[188:191], v[14:15], off offset:1024
	global_load_dwordx4 v[192:195], v[10:11], off
	v_lshl_add_u64 v[154:155], v[52:53], 0, v[20:21]
	global_load_dwordx4 v[196:199], v[154:155], off
	s_waitcnt vmcnt(15)
	v_and_b32_e32 v57, 0xffff0000, v44
	s_waitcnt vmcnt(14)
	v_and_b32_e32 v59, 0xffff0000, v46
	v_lshlrev_b32_e32 v56, 16, v44
	v_lshlrev_b32_e32 v58, 16, v46
	s_waitcnt vmcnt(13)
	v_and_b32_e32 v61, 0xffff0000, v48
	s_waitcnt vmcnt(12)
	v_and_b32_e32 v63, 0xffff0000, v50
	v_mov_b32_e32 v66, v57
	v_mov_b32_e32 v67, v59
	v_lshlrev_b32_e32 v44, 16, v45
	v_lshlrev_b32_e32 v46, 16, v47
	v_lshlrev_b32_e32 v60, 16, v48
	v_lshlrev_b32_e32 v62, 16, v50
	v_mov_b32_e32 v64, v56
	v_mov_b32_e32 v65, v58
	v_mov_b32_e32 v74, v61
	v_mov_b32_e32 v75, v63
	v_pk_mul_f32 v[66:67], v[66:67], v[66:67]
	v_and_b32_e32 v45, 0xffff0000, v45
	v_and_b32_e32 v47, 0xffff0000, v47
	v_lshlrev_b32_e32 v48, 16, v49
	v_lshlrev_b32_e32 v50, 16, v51
	v_mov_b32_e32 v68, v44
	v_mov_b32_e32 v69, v46
	v_mov_b32_e32 v72, v60
	v_mov_b32_e32 v73, v62
	v_pk_mul_f32 v[74:75], v[74:75], v[74:75]
	v_pk_fma_f32 v[64:65], v[64:65], v[64:65], v[66:67]
	v_and_b32_e32 v49, 0xffff0000, v49
	v_and_b32_e32 v51, 0xffff0000, v51
	v_mov_b32_e32 v70, v45
	v_mov_b32_e32 v71, v47
	v_mov_b32_e32 v76, v48
	v_mov_b32_e32 v77, v50
	v_pk_fma_f32 v[66:67], v[72:73], v[72:73], v[74:75]
	v_pk_fma_f32 v[64:65], v[68:69], v[68:69], v[64:65]
	v_mov_b32_e32 v78, v49
	v_mov_b32_e32 v79, v51
	v_pk_fma_f32 v[66:67], v[76:77], v[76:77], v[66:67]
	v_pk_fma_f32 v[64:65], v[70:71], v[70:71], v[64:65]
	v_pk_fma_f32 v[66:67], v[78:79], v[78:79], v[66:67]
	v_add_f32_e32 v64, v64, v65
	v_add_f32_e32 v64, v64, v66
	v_add_f32_e32 v64, v64, v67
	ds_bpermute_b32 v65, v22, v64
	s_waitcnt lgkmcnt(0)
	v_add_f32_e32 v64, v64, v65
	ds_bpermute_b32 v65, v23, v64
	s_waitcnt lgkmcnt(0)
	v_add_f32_e32 v64, v64, v65
	ds_bpermute_b32 v65, v24, v64
	s_waitcnt lgkmcnt(0)
	v_add_f32_e32 v64, v64, v65
	ds_bpermute_b32 v65, v25, v64
	s_waitcnt lgkmcnt(0)
	v_add_f32_e32 v64, v64, v65
	ds_bpermute_b32 v65, v26, v64
	s_waitcnt lgkmcnt(0)
	v_add_f32_e32 v64, v64, v65
	ds_bpermute_b32 v65, v27, v64
	s_waitcnt lgkmcnt(0)
	v_add_f32_e32 v64, v64, v65
	v_fmamk_f32 v64, v64, 0x3a800000, v1
	v_mul_f32_e32 v65, 0x4b800000, v64
	v_cmp_gt_f32_e32 vcc, s12, v64
	s_nop 1
	v_cndmask_b32_e32 v64, v64, v65, vcc
	v_rsq_f32_e32 v64, v64
	s_nop 0
	v_mul_f32_e32 v65, 0x45800000, v64
	v_cndmask_b32_e32 v64, v64, v65, vcc
	v_pk_mul_f32 v[56:57], v[64:65], v[56:57] op_sel_hi:[0,1]
	v_pk_mul_f32 v[44:45], v[64:65], v[44:45] op_sel_hi:[0,1]
	s_waitcnt vmcnt(11)
	v_pk_mul_f32 v[28:29], v[28:29], v[56:57]
	v_pk_mul_f32 v[30:31], v[30:31], v[44:45]
	s_waitcnt vmcnt(8)
	v_pk_fma_f32 v[28:29], v[40:41], v[28:29], v[32:33]
	v_pk_fma_f32 v[30:31], v[42:43], v[30:31], v[34:35]
	global_store_dwordx4 v[14:15], v[28:31], off offset:-2048
	s_nop 0
	v_pk_mul_f32 v[54:55], v[64:65], v[58:59] op_sel_hi:[0,1]
	v_pk_mul_f32 v[46:47], v[64:65], v[46:47] op_sel_hi:[0,1]
	v_lshl_add_u64 v[44:45], v[52:53], 0, v[18:19]
	v_pk_mul_f32 v[48:49], v[64:65], v[48:49] op_sel_hi:[0,1]
	v_cmp_lt_i32_e32 vcc, s13, v0
	s_or_b64 s[8:9], vcc, s[8:9]
	s_waitcnt vmcnt(8)
	v_pk_mul_f32 v[28:29], v[54:55], v[144:145]
	v_pk_mul_f32 v[30:31], v[46:47], v[146:147]
	s_waitcnt vmcnt(7)
	v_pk_fma_f32 v[28:29], v[148:149], v[28:29], v[36:37]
	v_pk_fma_f32 v[30:31], v[150:151], v[30:31], v[38:39]
	global_store_dwordx4 v[14:15], v[28:31], off offset:-1024
	s_nop 0
	v_pk_mul_f32 v[46:47], v[64:65], v[60:61] op_sel_hi:[0,1]
	v_lshl_add_u64 v[44:45], v[52:53], 0, v[20:21]
	s_waitcnt vmcnt(6)
	v_pk_mul_f32 v[28:29], v[46:47], v[164:165]
	v_pk_mul_f32 v[30:31], v[48:49], v[166:167]
	s_waitcnt vmcnt(5)
	v_pk_fma_f32 v[28:29], v[168:169], v[28:29], v[156:157]
	v_pk_fma_f32 v[30:31], v[170:171], v[30:31], v[158:159]
	global_store_dwordx4 v[14:15], v[28:31], off
	s_nop 0
	v_pk_mul_f32 v[40:41], v[64:65], v[62:63] op_sel_hi:[0,1]
	v_pk_mul_f32 v[42:43], v[64:65], v[50:51] op_sel_hi:[0,1]
	s_waitcnt vmcnt(4)
	v_pk_mul_f32 v[28:29], v[40:41], v[192:193]
	v_pk_mul_f32 v[30:31], v[42:43], v[194:195]
	s_waitcnt vmcnt(3)
	v_pk_fma_f32 v[28:29], v[196:197], v[28:29], v[188:189]
	v_pk_fma_f32 v[30:31], v[198:199], v[30:31], v[190:191]
	global_store_dwordx4 v[14:15], v[28:31], off offset:1024
	v_lshl_add_u64 v[14:15], v[14:15], 0, s[6:7]
	s_andn2_b64 exec, exec, s[8:9]
	s_cbranch_execnz .LBB0_2296
